# ctx attention row-max: 58 more canonicalising self-max ops folded into their consumer (s_nop 0 in place)
# baseline (speedup 1.0000x reference)
.LBB0_1402:
	s_add_u32 s0, s46, 0x8bfe000
	s_addc_u32 s1, s47, 0
	v_lshlrev_b64 v[34:35], 11, v[112:113]
	v_lshl_add_u64 v[34:35], s[0:1], 0, v[34:35]
	v_lshl_add_u64 v[34:35], v[34:35], 0, s[12:13]
	v_lshl_add_u64 v[34:35], v[192:193], 1, v[34:35]
	v_mov_b64_e32 v[36:37], v[160:161]
	v_mov_b64_e32 v[38:39], v[162:163]
	v_mov_b64_e32 v[40:41], v[164:165]
	v_mov_b64_e32 v[42:43], v[166:167]
	v_mov_b64_e32 v[44:45], v[168:169]
	v_cmp_lt_i32_e32 vcc, v222, v221
	v_mov_b64_e32 v[46:47], v[170:171]
	v_lshlrev_b32_e32 v140, 3, v69
	v_cndmask_b32_e32 v33, v220, v222, vcc
	v_lshlrev_b32_e32 v210, 2, v33
	ds_bpermute_b32 v33, v210, v32
	s_waitcnt lgkmcnt(0)
	v_add_f32_e32 v50, v32, v33
	v_mov_b64_e32 v[32:33], v[172:173]
	v_mov_b64_e32 v[48:49], v[174:175]
	v_div_scale_f32 v51, s[4:5], v50, v50, 1.0
	v_rcp_f32_e32 v52, v51
	v_div_scale_f32 v53, vcc, 1.0, v50, 1.0
	v_readlane_b32 s4, v254, 52
	v_fma_f32 v54, -v51, v52, 1.0
	v_fmac_f32_e32 v52, v54, v52
	v_mul_f32_e32 v54, v53, v52
	v_fma_f32 v55, -v51, v54, v53
	v_fmac_f32_e32 v54, v55, v52
	v_fma_f32 v51, -v51, v54, v53
	v_div_fmas_f32 v51, v51, v52, v54
	v_div_fixup_f32 v50, v51, v50, 1.0
	v_pk_mul_f32 v[16:17], v[16:17], v[50:51] op_sel_hi:[1,0]
	v_pk_mul_f32 v[18:19], v[18:19], v[50:51] op_sel_hi:[1,0]
	v_pk_mul_f32 v[0:1], v[0:1], v[50:51] op_sel_hi:[1,0]
	v_pk_mul_f32 v[2:3], v[2:3], v[50:51] op_sel_hi:[1,0]
	v_pk_mul_f32 v[20:21], v[20:21], v[50:51] op_sel_hi:[1,0]
	v_pk_mul_f32 v[22:23], v[22:23], v[50:51] op_sel_hi:[1,0]
	v_pk_mul_f32 v[24:25], v[24:25], v[50:51] op_sel_hi:[1,0]
	v_pk_mul_f32 v[26:27], v[26:27], v[50:51] op_sel_hi:[1,0]
	v_pk_mul_f32 v[28:29], v[28:29], v[50:51] op_sel_hi:[1,0]
	v_pk_mul_f32 v[30:31], v[30:31], v[50:51] op_sel_hi:[1,0]
	v_pk_mul_f32 v[4:5], v[4:5], v[50:51] op_sel_hi:[1,0]
	v_readlane_b32 s5, v254, 53
	s_andn2_b64 vcc, exec, s[4:5]
	s_waitcnt vmcnt(7)
	v_lshlrev_b32_e32 v52, 16, v36
	v_and_b32_e32 v53, 0xffff0000, v36
	v_lshlrev_b32_e32 v36, 16, v37
	v_and_b32_e32 v37, 0xffff0000, v37
	s_waitcnt vmcnt(3)
	v_lshlrev_b32_e32 v60, 16, v44
	v_and_b32_e32 v61, 0xffff0000, v44
	v_lshlrev_b32_e32 v44, 16, v45
	v_and_b32_e32 v45, 0xffff0000, v45
	v_lshlrev_b32_e32 v54, 16, v38
	v_and_b32_e32 v55, 0xffff0000, v38
	v_lshlrev_b32_e32 v38, 16, v39
	v_and_b32_e32 v39, 0xffff0000, v39
	v_lshlrev_b32_e32 v56, 16, v40
	v_and_b32_e32 v57, 0xffff0000, v40
	v_lshlrev_b32_e32 v40, 16, v41
	v_and_b32_e32 v41, 0xffff0000, v41
	v_lshlrev_b32_e32 v58, 16, v42
	v_and_b32_e32 v59, 0xffff0000, v42
	v_lshlrev_b32_e32 v42, 16, v43
	v_and_b32_e32 v43, 0xffff0000, v43
	v_pk_mul_f32 v[16:17], v[16:17], v[52:53]
	v_pk_mul_f32 v[18:19], v[18:19], v[36:37]
	v_pk_mul_f32 v[0:1], v[0:1], v[60:61]
	v_pk_mul_f32 v[2:3], v[2:3], v[44:45]
	v_pk_mul_f32 v[20:21], v[20:21], v[54:55]
	v_pk_mul_f32 v[22:23], v[22:23], v[38:39]
	v_pk_mul_f32 v[24:25], v[24:25], v[56:57]
	v_pk_mul_f32 v[26:27], v[26:27], v[40:41]
	v_pk_mul_f32 v[28:29], v[28:29], v[58:59]
	v_pk_mul_f32 v[30:31], v[30:31], v[42:43]
	v_cvt_pk_bf16_f32 v16, v16, v17
	v_cvt_pk_bf16_f32 v17, v18, v19
	v_cvt_pk_bf16_f32 v0, v0, v1
	v_cvt_pk_bf16_f32 v1, v2, v3
	v_cvt_pk_bf16_f32 v18, v20, v21
	v_cvt_pk_bf16_f32 v19, v22, v23
	v_cvt_pk_bf16_f32 v20, v24, v25
	v_cvt_pk_bf16_f32 v21, v26, v27
	v_cvt_pk_bf16_f32 v22, v28, v29
	v_cvt_pk_bf16_f32 v23, v30, v31
	global_store_dwordx2 v[34:35], v[16:17], off
	global_store_dwordx2 v[34:35], v[18:19], off offset:16
	global_store_dwordx2 v[34:35], v[20:21], off offset:32
	global_store_dwordx2 v[34:35], v[22:23], off offset:48
	global_store_dwordx2 v[34:35], v[0:1], off offset:64
	s_waitcnt vmcnt(7)
	v_lshlrev_b32_e32 v0, 16, v46
	v_and_b32_e32 v1, 0xffff0000, v46
	v_pk_mul_f32 v[0:1], v[4:5], v[0:1]
	v_pk_mul_f32 v[2:3], v[6:7], v[50:51] op_sel_hi:[1,0]
	v_lshlrev_b32_e32 v4, 16, v47
	v_and_b32_e32 v5, 0xffff0000, v47
	v_pk_mul_f32 v[2:3], v[2:3], v[4:5]
	v_cvt_pk_bf16_f32 v0, v0, v1
	v_cvt_pk_bf16_f32 v1, v2, v3
	global_store_dwordx2 v[34:35], v[0:1], off offset:80
	v_pk_mul_f32 v[0:1], v[8:9], v[50:51] op_sel_hi:[1,0]
	s_waitcnt vmcnt(7)
	v_lshlrev_b32_e32 v2, 16, v32
	v_and_b32_e32 v3, 0xffff0000, v32
	v_pk_mul_f32 v[0:1], v[0:1], v[2:3]
	v_pk_mul_f32 v[2:3], v[10:11], v[50:51] op_sel_hi:[1,0]
	v_lshlrev_b32_e32 v4, 16, v33
	v_and_b32_e32 v5, 0xffff0000, v33
	v_pk_mul_f32 v[2:3], v[2:3], v[4:5]
	v_cvt_pk_bf16_f32 v0, v0, v1
	v_cvt_pk_bf16_f32 v1, v2, v3
	global_store_dwordx2 v[34:35], v[0:1], off offset:96
	v_pk_mul_f32 v[0:1], v[12:13], v[50:51] op_sel_hi:[1,0]
	s_waitcnt vmcnt(7)
	v_lshlrev_b32_e32 v2, 16, v48
	v_and_b32_e32 v3, 0xffff0000, v48
	v_pk_mul_f32 v[0:1], v[0:1], v[2:3]
	v_pk_mul_f32 v[2:3], v[14:15], v[50:51] op_sel_hi:[1,0]
	v_lshlrev_b32_e32 v4, 16, v49
	v_and_b32_e32 v5, 0xffff0000, v49
	v_pk_mul_f32 v[2:3], v[2:3], v[4:5]
	v_cvt_pk_bf16_f32 v0, v0, v1
	v_cvt_pk_bf16_f32 v1, v2, v3
	global_store_dwordx2 v[34:35], v[0:1], off offset:112
	s_cbranch_vccnz .LBB0_1405
	s_lshl_b32 s4, s54, 5
	v_readlane_b32 s10, v254, 54
	s_add_i32 s5, s4, s10
	v_readlane_b32 s16, v255, 13
	v_readlane_b32 s11, v254, 55
	v_readlane_b32 s17, v255, 14
	s_add_u32 s10, s50, s16
	s_addc_u32 s11, s51, s17
	s_add_u32 s16, s36, s16
	s_addc_u32 s17, s37, s17
	v_lshlrev_b64 v[54:55], 10, v[132:133]
	v_lshl_add_u64 v[0:1], s[10:11], 0, v[54:55]
	v_mov_b32_e32 v111, v193
	v_lshl_add_u64 v[2:3], s[16:17], 0, v[54:55]
	v_lshl_add_u64 v[0:1], v[0:1], 0, v[110:111]
	v_lshl_add_u64 v[4:5], v[2:3], 0, v[110:111]
	global_load_dwordx4 v[0:3], v[0:1], off
	s_nop 0
	global_load_dwordx4 v[4:7], v[4:5], off
	v_or_b32_e32 v142, s5, v135
	v_ashrrev_i32_e32 v143, 31, v142
	v_readlane_b32 s18, v255, 33
	v_lshlrev_b64 v[8:9], 10, v[142:143]
	v_readlane_b32 s19, v255, 34
	v_lshl_add_u64 v[8:9], s[20:21], 0, v[8:9]
	s_mov_b32 s19, s13
	v_lshlrev_b64 v[234:235], 11, v[142:143]
	v_mov_b32_e32 v224, v140
	v_mov_b32_e32 v225, 0
	v_lshl_add_u64 v[234:235], s[0:1], 0, v[234:235]
	v_lshl_add_u64 v[234:235], v[234:235], 0, s[18:19]
	v_lshl_add_u64 v[234:235], v[234:235], 0, v[224:225]
	global_load_dwordx2 v[224:225], v[234:235], off
	global_load_dwordx2 v[226:227], v[234:235], off offset:16
	global_load_dwordx2 v[246:247], v[234:235], off offset:32
	global_load_dwordx2 v[248:249], v[234:235], off offset:48
	global_load_dwordx2 v[214:215], v[234:235], off offset:64
	global_load_dwordx2 v[216:217], v[234:235], off offset:80
	global_load_dwordx2 v[230:231], v[234:235], off offset:96
	global_load_dwordx2 v[232:233], v[234:235], off offset:112
	v_mov_b32_e32 v234, 0x7ffff800
	v_mov_b32_e32 v235, 0xffffff00
	v_lshl_add_u64 v[8:9], v[8:9], 0, s[18:19]
	v_lshlrev_b32_e32 v192, 1, v140
	v_lshl_add_u64 v[8:9], v[8:9], 0, v[192:193]
	global_load_dwordx4 v[92:95], v[8:9], off
	global_load_dwordx4 v[88:91], v[8:9], off offset:32
	global_load_dwordx4 v[84:87], v[8:9], off offset:64
	global_load_dwordx4 v[96:99], v[8:9], off offset:96
	v_readlane_b32 s16, v255, 15
	v_readlane_b32 s17, v255, 16
	s_add_u32 s10, s50, s16
	s_addc_u32 s11, s51, s17
	s_add_u32 s16, s36, s16
	v_lshl_add_u64 v[8:9], s[10:11], 0, v[54:55]
	s_addc_u32 s17, s37, s17
	v_lshl_add_u64 v[8:9], v[8:9], 0, v[110:111]
	v_lshl_add_u64 v[10:11], s[16:17], 0, v[54:55]
	v_lshl_add_u64 v[10:11], v[10:11], 0, v[110:111]
	global_load_dwordx4 v[16:19], v[8:9], off
	global_load_dwordx4 v[38:41], v[10:11], off
	v_readlane_b32 s16, v255, 17
	v_readlane_b32 s17, v255, 18
	s_add_u32 s10, s50, s16
	s_addc_u32 s11, s51, s17
	s_add_u32 s16, s36, s16
	v_lshl_add_u32 v237, v69, 4, 0
	s_movk_i32 s5, 0x90
	v_lshl_add_u64 v[8:9], s[10:11], 0, v[54:55]
	s_addc_u32 s17, s37, s17
	v_mad_u32_u24 v141, v209, s5, v237
	v_lshl_add_u64 v[8:9], v[8:9], 0, v[110:111]
	v_lshl_add_u64 v[10:11], s[16:17], 0, v[54:55]
	v_lshl_add_u64 v[10:11], v[10:11], 0, v[110:111]
	global_load_dwordx4 v[66:69], v[8:9], off
	global_load_dwordx4 v[70:73], v[10:11], off
	s_barrier
	v_mad_u32_u24 v238, v135, s5, v237
	v_readlane_b32 s10, v255, 19
	v_readlane_b32 s11, v255, 20
	s_waitcnt vmcnt(9)
	ds_write_b128 v207, v[0:3] offset:15360
	s_waitcnt vmcnt(8)
	ds_write_b128 v207, v[4:7] offset:24576
	s_waitcnt lgkmcnt(0)
	s_barrier
	ds_read_b128 v[0:3], v141 offset:15360
	ds_read_b128 v[42:45], v141 offset:15392
	s_waitcnt vmcnt(7) lgkmcnt(1)
	v_mfma_f32_32x32x16_bf16 v[0:15], v[0:3], v[92:95], 0
	ds_read_b128 v[20:23], v238 offset:15360
	ds_read_b128 v[46:49], v238 offset:15392
	s_waitcnt lgkmcnt(1)
	v_mfma_f32_32x32x16_bf16 v[22:37], v[20:23], v[92:95], 0
	v_lshl_add_u64 v[20:21], s[50:51], 0, v[54:55]
	v_lshl_add_u64 v[136:137], v[20:21], 0, v[110:111]
	s_waitcnt vmcnt(6)
	v_mfma_f32_32x32x16_bf16 v[0:15], v[42:45], v[88:91], v[0:15]
	s_waitcnt lgkmcnt(0)
	v_mfma_f32_32x32x16_bf16 v[22:37], v[46:49], v[88:91], v[22:37]
	ds_read_b128 v[42:45], v141 offset:15424
	ds_read_b128 v[46:49], v141 offset:15456
	s_waitcnt vmcnt(5) lgkmcnt(1)
	v_mfma_f32_32x32x16_bf16 v[0:15], v[42:45], v[84:87], v[0:15]
	ds_read_b128 v[42:45], v238 offset:15424
	ds_read_b128 v[50:53], v238 offset:15456
	s_waitcnt lgkmcnt(1)
	v_mfma_f32_32x32x16_bf16 v[22:37], v[42:45], v[84:87], v[22:37]
	v_lshl_add_u64 v[42:43], s[36:37], 0, v[54:55]
	v_lshl_add_u64 v[138:139], v[42:43], 0, v[110:111]
	v_lshlrev_b32_e32 v44, 1, v120
	v_mul_u32_u24_e32 v45, 0x90, v115
	v_add3_u32 v211, 0, v44, v45
	s_waitcnt vmcnt(4) lgkmcnt(0)
	v_mfma_f32_32x32x16_bf16 v[22:37], v[50:53], v[96:99], v[22:37]
	v_mfma_f32_32x32x16_bf16 v[0:15], v[46:49], v[96:99], v[0:15]
	s_nop 10
	s_nop 0
	s_nop 0
	s_nop 0
	s_nop 0
	v_max_f32_e32 v20, v22, v23
	v_max_f32_e32 v21, v24, v25
	s_nop 0
	s_nop 0
	s_nop 0
	s_nop 0
	s_nop 0
	s_nop 0
	s_nop 0
	s_nop 0
	v_max_f32_e32 v42, v0, v1
	v_max_f32_e32 v43, v2, v3
	v_max3_f32 v20, v20, s23, v21
	s_nop 0
	s_nop 0
	s_nop 0
	s_nop 0
	v_max_f32_e32 v46, v26, v27
	v_max_f32_e32 v47, v28, v29
	v_max3_f32 v20, v20, v42, v43
	v_max_f32_e32 v58, v31, v31
	v_max_f32_e32 v59, v30, v30
	v_max_f32_e32 v60, v33, v33
	v_max_f32_e32 v61, v32, v32
	v_max_f32_e32 v48, v4, v5
	v_max_f32_e32 v49, v6, v7
	v_max3_f32 v20, v20, v46, v47
	v_max_f32_e32 v62, v9, v9
	v_max_f32_e32 v63, v8, v8
	v_max_f32_e32 v64, v11, v11
	v_max_f32_e32 v65, v10, v10
	v_max_f32_e32 v50, v59, v58
	v_max_f32_e32 v51, v61, v60
	v_max3_f32 v20, v20, v48, v49
	s_nop 0
	s_nop 0
	s_nop 0
	s_nop 0
	v_max_f32_e32 v52, v63, v62
	v_max_f32_e32 v53, v65, v64
	v_max3_f32 v20, v20, v50, v51
	s_nop 0
	s_nop 0
	s_nop 0
	s_nop 0
	v_max_f32_e32 v54, v34, v35
	v_max_f32_e32 v55, v36, v37
	v_max3_f32 v20, v20, v52, v53
	v_max_f32_e32 v56, v12, v13
	v_max_f32_e32 v57, v14, v15
	v_max3_f32 v20, v20, v54, v55
	v_max3_f32 v46, v20, v56, v57
	ds_bpermute_b32 v47, v210, v46
	v_lshl_add_u64 v[42:43], v[136:137], 0, s[10:11]
	v_lshl_add_u64 v[20:21], v[138:139], 0, s[10:11]
	global_load_dwordx4 v[100:103], v[42:43], off
	global_load_dwordx4 v[104:107], v[20:21], off
	ds_read_b64_tr_b16 v[128:129], v211 offset:24576
	ds_read_b64_tr_b16 v[130:131], v211 offset:25728
	ds_read_b64_tr_b16 v[126:127], v211 offset:25792
	ds_read_b64_tr_b16 v[124:125], v211 offset:24640
	ds_read_b64_tr_b16 v[120:121], v211 offset:26880
	ds_read_b64_tr_b16 v[122:123], v211 offset:28032
	ds_read_b64_tr_b16 v[118:119], v211 offset:28096
	ds_read_b64_tr_b16 v[116:117], v211 offset:26944
	ds_read_b64_tr_b16 v[112:113], v211 offset:29184
	ds_read_b64_tr_b16 v[114:115], v211 offset:30336
	ds_read_b64_tr_b16 v[110:111], v211 offset:30400
	ds_read_b64_tr_b16 v[108:109], v211 offset:29248
	ds_read_b64_tr_b16 v[78:79], v211 offset:31488
	ds_read_b64_tr_b16 v[80:81], v211 offset:32640
	ds_read_b64_tr_b16 v[76:77], v211 offset:32704
	ds_read_b64_tr_b16 v[74:75], v211 offset:31552
	s_waitcnt lgkmcnt(14)
	v_max3_f32 v52, v46, v47, s23
	v_sub_f32_e32 v0, v0, v52
	v_exp_f32_e32 v150, v0
	v_sub_f32_e32 v0, v1, v52
	v_exp_f32_e32 v154, v0
	v_sub_f32_e32 v0, v2, v52
	v_exp_f32_e32 v144, v0
	v_sub_f32_e32 v0, v3, v52
	v_exp_f32_e32 v148, v0
	v_sub_f32_e32 v0, v26, v52
	v_exp_f32_e32 v152, v0
	v_sub_f32_e32 v0, v27, v52
	v_exp_f32_e32 v156, v0
	v_sub_f32_e32 v0, v28, v52
	v_exp_f32_e32 v160, v0
	v_sub_f32_e32 v0, v29, v52
	v_exp_f32_e32 v162, v0
	v_sub_f32_e32 v0, v4, v52
	v_exp_f32_e32 v158, v0
	v_sub_f32_e32 v0, v5, v52
	v_exp_f32_e32 v164, v0
	s_waitcnt vmcnt(5)
	ds_write_b128 v207, v[16:19] offset:33792
	s_waitcnt vmcnt(4)
	ds_write_b128 v207, v[38:41] offset:43008
	s_waitcnt lgkmcnt(0)
	s_barrier
	ds_read_b128 v[0:3], v141 offset:33792
	v_sub_f32_e32 v4, v6, v52
	v_exp_f32_e32 v168, v4
	v_sub_f32_e32 v4, v7, v52
	v_sub_f32_e32 v20, v22, v52
	v_exp_f32_e32 v170, v4
	v_sub_f32_e32 v4, v30, v52
	v_sub_f32_e32 v21, v23, v52
	v_sub_f32_e32 v22, v24, v52
	v_exp_f32_e32 v240, v20
	v_sub_f32_e32 v20, v25, v52
	v_exp_f32_e32 v172, v4
	ds_read_b128 v[4:7], v141 offset:33824
	v_exp_f32_e32 v239, v21
	v_exp_f32_e32 v82, v22
	v_exp_f32_e32 v146, v20
	v_sub_f32_e32 v38, v31, v52
	s_waitcnt lgkmcnt(1)
	v_mfma_f32_32x32x16_bf16 v[16:31], v[0:3], v[92:95], 0
	v_sub_f32_e32 v0, v32, v52
	v_exp_f32_e32 v174, v0
	v_sub_f32_e32 v0, v33, v52
	v_exp_f32_e32 v176, v0
	ds_read_b128 v[0:3], v141 offset:33856
	v_sub_f32_e32 v8, v8, v52
	v_exp_f32_e32 v180, v8
	s_waitcnt lgkmcnt(1)
	v_mfma_f32_32x32x16_bf16 v[16:31], v[4:7], v[88:91], v[16:31]
	v_sub_f32_e32 v4, v9, v52
	v_exp_f32_e32 v182, v4
	v_sub_f32_e32 v4, v10, v52
	v_exp_f32_e32 v184, v4
	ds_read_b128 v[4:7], v141 offset:33888
	v_sub_f32_e32 v8, v11, v52
	v_exp_f32_e32 v178, v38
	s_waitcnt lgkmcnt(1)
	v_mfma_f32_32x32x16_bf16 v[16:31], v[0:3], v[84:87], v[16:31]
	v_sub_f32_e32 v0, v34, v52
	v_exp_f32_e32 v186, v0
	v_sub_f32_e32 v0, v35, v52
	v_exp_f32_e32 v188, v0
	ds_read_b128 v[0:3], v238 offset:33792
	v_exp_f32_e32 v190, v8
	v_sub_f32_e32 v8, v36, v52
	s_waitcnt lgkmcnt(1)
	v_mfma_f32_32x32x16_bf16 v[16:31], v[4:7], v[96:99], v[16:31]
	v_sub_f32_e32 v4, v37, v52
	v_exp_f32_e32 v198, v4
	v_sub_f32_e32 v4, v12, v52
	v_exp_f32_e32 v200, v4
	ds_read_b128 v[4:7], v238 offset:33824
	v_exp_f32_e32 v196, v8
	v_sub_f32_e32 v8, v13, v52
	s_waitcnt lgkmcnt(1)
	v_mfma_f32_32x32x16_bf16 v[32:47], v[0:3], v[92:95], 0
	v_exp_f32_e32 v202, v8
	ds_read_b128 v[8:11], v238 offset:33856
	v_sub_f32_e32 v48, 0xf149f2ca, v52
	v_exp_f32_e32 v1, v48
	ds_read_b128 v[48:51], v238 offset:33888
	v_sub_f32_e32 v0, v14, v52
	v_exp_f32_e32 v204, v0
	s_waitcnt lgkmcnt(2)
	v_mfma_f32_32x32x16_bf16 v[32:47], v[4:7], v[88:91], v[32:47]
	v_sub_f32_e32 v0, v15, v52
	v_exp_f32_e32 v166, v0
	v_mul_f32_e32 v0, 0, v1
	v_mov_b32_e32 v1, v0
	v_mov_b32_e32 v2, v0
	v_mov_b32_e32 v3, v0
	v_mov_b32_e32 v4, v0
	s_waitcnt lgkmcnt(1)
	v_mfma_f32_32x32x16_bf16 v[32:47], v[8:11], v[84:87], v[32:47]
	v_mov_b32_e32 v5, v0
	v_mov_b32_e32 v6, v0
	v_mov_b32_e32 v7, v0
	v_mov_b32_e32 v8, v0
	v_mov_b32_e32 v9, v0
	v_mov_b32_e32 v10, v0
	v_mov_b32_e32 v11, v0
	s_waitcnt lgkmcnt(0)
	v_mfma_f32_32x32x16_bf16 v[32:47], v[48:51], v[96:99], v[32:47]
	s_nop 0
	v_mov_b32_e32 v12, v0
	v_cvt_pk_bf16_f32 v242, v240, v239
	v_cvt_pk_bf16_f32 v243, v82, v146
	v_cvt_pk_bf16_f32 v244, v152, v156
	v_cvt_pk_bf16_f32 v245, v160, v162
	s_mov_b32 s10, s18
	s_nop 4
	s_nop 1
	v_max_f32_e32 v13, v32, v33
	s_nop 1
	v_max_f32_e32 v14, v34, v35
	v_max3_f32 v13, v13, s23, v14
	s_nop 1
	v_max_f32_e32 v14, v16, v17
	s_nop 0
	v_max_f32_e32 v15, v18, v19
	v_max3_f32 v13, v13, v14, v15
	s_nop 1
	v_max_f32_e32 v14, v36, v37
	s_nop 1
	v_max_f32_e32 v15, v38, v39
	v_max3_f32 v13, v13, v14, v15
	s_nop 1
	v_max_f32_e32 v14, v20, v21
	s_nop 1
	v_max_f32_e32 v15, v22, v23
	v_max3_f32 v13, v13, v14, v15
	s_nop 1
	v_max_f32_e32 v14, v40, v41
	s_nop 1
	v_max_f32_e32 v15, v42, v43
	v_max3_f32 v13, v13, v14, v15
	s_nop 1
	v_max_f32_e32 v14, v24, v25
	s_nop 1
	v_max_f32_e32 v15, v26, v27
	v_max3_f32 v13, v13, v14, v15
	s_nop 1
	v_max_f32_e32 v14, v44, v45
	s_nop 1
	v_max_f32_e32 v15, v46, v47
	v_max3_f32 v13, v13, v14, v15
	s_nop 1
	v_max_f32_e32 v14, v28, v29
	s_nop 1
	v_max_f32_e32 v15, v30, v31
	v_max3_f32 v48, v13, v14, v15
	ds_bpermute_b32 v49, v210, v48
	v_mov_b32_e32 v13, v0
	v_mov_b32_e32 v14, v0
	v_mov_b32_e32 v15, v0
	v_writelane_b32 v255, s10, 33
	s_waitcnt lgkmcnt(0)
	v_max3_f32 v241, v52, v48, v49
	v_sub_f32_e32 v16, v16, v241
	v_exp_f32_e32 v145, v16
	v_sub_f32_e32 v16, v17, v241
	v_exp_f32_e32 v149, v16
	v_sub_f32_e32 v16, v18, v241
	v_exp_f32_e32 v153, v16
	v_sub_f32_e32 v16, v19, v241
	v_exp_f32_e32 v157, v16
	v_sub_f32_e32 v16, v36, v241
	v_exp_f32_e32 v161, v16
	v_sub_f32_e32 v16, v37, v241
	v_exp_f32_e32 v163, v16
	v_sub_f32_e32 v16, v38, v241
	v_exp_f32_e32 v159, v16
	v_sub_f32_e32 v16, v39, v241
	v_exp_f32_e32 v165, v16
	v_sub_f32_e32 v16, v20, v241
	v_exp_f32_e32 v169, v16
	v_sub_f32_e32 v16, v21, v241
	v_sub_f32_e32 v48, v52, v241
	v_mfma_f32_32x32x16_bf16 v[50:65], v[128:131], v[242:245], v[0:15]
	v_exp_f32_e32 v171, v16
	v_mov_b64_e32 v[16:17], v[14:15]
	v_sub_f32_e32 v18, v22, v241
	v_exp_f32_e32 v173, v18
	v_cvt_pk_bf16_f32 v18, v172, v178
	s_nop 1
	v_mov_b64_e32 v[14:15], v[12:13]
	v_mov_b64_e32 v[12:13], v[10:11]
	v_mov_b64_e32 v[10:11], v[8:9]
	v_mov_b64_e32 v[8:9], v[6:7]
	v_mov_b64_e32 v[6:7], v[4:5]
	v_mov_b64_e32 v[4:5], v[2:3]
	v_mov_b64_e32 v[2:3], v[0:1]
	v_cvt_pk_bf16_f32 v19, v174, v176
	v_cvt_pk_bf16_f32 v20, v186, v188
	v_mfma_f32_32x32x16_bf16 v[2:17], v[124:127], v[242:245], v[2:17]
	v_cvt_pk_bf16_f32 v21, v196, v198
	v_sub_f32_e32 v1, v23, v241
	v_exp_f32_e32 v179, v1
	v_sub_f32_e32 v1, v40, v241
	v_cvt_pk_bf16_f32 v22, v200, v202
	v_cvt_pk_bf16_f32 v23, v204, v166
	v_sub_f32_e32 v32, v32, v241
	v_mfma_f32_32x32x16_bf16 v[50:65], v[120:123], v[18:21], v[50:65]
	v_exp_f32_e32 v175, v1
	v_sub_f32_e32 v1, v41, v241
	v_exp_f32_e32 v83, v32
	v_sub_f32_e32 v32, v33, v241
	v_exp_f32_e32 v177, v1
	v_sub_f32_e32 v1, v42, v241
	v_exp_f32_e32 v147, v32
	v_mfma_f32_32x32x16_bf16 v[2:17], v[116:119], v[18:21], v[2:17]
	v_cvt_pk_bf16_f32 v18, v150, v154
	v_cvt_pk_bf16_f32 v19, v144, v148
	v_cvt_pk_bf16_f32 v20, v158, v164
	v_cvt_pk_bf16_f32 v21, v168, v170
	v_sub_f32_e32 v32, v34, v241
	v_exp_f32_e32 v181, v1
	v_sub_f32_e32 v1, v43, v241
	v_mfma_f32_32x32x16_bf16 v[50:65], v[112:115], v[18:21], v[50:65]
	v_exp_f32_e32 v151, v32
	v_sub_f32_e32 v32, v35, v241
	v_exp_f32_e32 v183, v1
	v_sub_f32_e32 v1, v24, v241
	v_exp_f32_e32 v155, v32
	v_exp_f32_e32 v185, v1
	v_sub_f32_e32 v1, v25, v241
	v_mfma_f32_32x32x16_bf16 v[2:17], v[108:111], v[18:21], v[2:17]
	v_cvt_pk_bf16_f32 v20, v180, v182
	v_cvt_pk_bf16_f32 v21, v184, v190
	v_exp_f32_e32 v18, v48
	v_exp_f32_e32 v191, v1
	v_sub_f32_e32 v1, v44, v241
	v_exp_f32_e32 v197, v1
	v_sub_f32_e32 v1, v45, v241
	v_mfma_f32_32x32x16_bf16 v[50:65], v[78:81], v[20:23], v[50:65]
	ds_read_b64_tr_b16 v[78:79], v211 offset:43008
	ds_read_b64_tr_b16 v[80:81], v211 offset:44160
	ds_read_b64_tr_b16 v[110:111], v211 offset:44224
	ds_read_b64_tr_b16 v[108:109], v211 offset:43072
	ds_read_b64_tr_b16 v[112:113], v211 offset:45312
	ds_read_b64_tr_b16 v[114:115], v211 offset:46464
	v_exp_f32_e32 v199, v1
	v_sub_f32_e32 v1, v46, v241
	v_exp_f32_e32 v201, v1
	v_sub_f32_e32 v1, v47, v241
	v_cvt_pk_bf16_f32 v116, v83, v147
	v_cvt_pk_bf16_f32 v117, v151, v155
	v_mfma_f32_32x32x16_bf16 v[2:17], v[74:77], v[20:23], v[2:17]
	v_cvt_pk_bf16_f32 v118, v161, v163
	v_cvt_pk_bf16_f32 v119, v159, v165
	v_mul_f32_e64 v48, v64, v18
	v_mul_f32_e64 v49, v65, v18
	v_mul_f32_e64 v46, v62, v18
	v_mul_f32_e64 v47, v63, v18
	v_pk_mul_f32 v[44:45], v[60:61], v[18:19] op_sel_hi:[1,0]
	v_pk_mul_f32 v[42:43], v[58:59], v[18:19] op_sel_hi:[1,0]
	v_pk_mul_f32 v[40:41], v[56:57], v[18:19] op_sel_hi:[1,0]
	v_pk_mul_f32 v[38:39], v[54:55], v[18:19] op_sel_hi:[1,0]
	v_pk_mul_f32 v[36:37], v[52:53], v[18:19] op_sel_hi:[1,0]
	v_pk_mul_f32 v[34:35], v[50:51], v[18:19] op_sel_hi:[1,0]
	v_pk_mul_f32 v[16:17], v[16:17], v[18:19] op_sel_hi:[1,0]
	v_pk_mul_f32 v[14:15], v[14:15], v[18:19] op_sel_hi:[1,0]
	v_pk_mul_f32 v[12:13], v[12:13], v[18:19] op_sel_hi:[1,0]
	v_pk_mul_f32 v[10:11], v[10:11], v[18:19] op_sel_hi:[1,0]
	v_pk_mul_f32 v[8:9], v[8:9], v[18:19] op_sel_hi:[1,0]
	v_pk_mul_f32 v[6:7], v[6:7], v[18:19] op_sel_hi:[1,0]
	v_pk_mul_f32 v[4:5], v[4:5], v[18:19] op_sel_hi:[1,0]
	v_pk_mul_f32 v[2:3], v[2:3], v[18:19] op_sel_hi:[1,0]
	s_waitcnt lgkmcnt(4)
	v_mfma_f32_32x32x16_bf16 v[34:49], v[78:81], v[116:119], v[34:49]
	v_exp_f32_e32 v203, v1
	ds_read_b64_tr_b16 v[22:23], v211 offset:46528
	ds_read_b64_tr_b16 v[20:21], v211 offset:45376
	v_cvt_pk_bf16_f32 v50, v175, v177
	v_cvt_pk_bf16_f32 v51, v181, v183
	v_cvt_pk_bf16_f32 v52, v197, v199
	v_cvt_pk_bf16_f32 v53, v201, v203
	v_sub_f32_e32 v1, v26, v241
	s_waitcnt lgkmcnt(4)
	v_mfma_f32_32x32x16_bf16 v[2:17], v[108:111], v[116:119], v[2:17]
	v_exp_f32_e32 v187, v1
	v_sub_f32_e32 v1, v27, v241
	ds_read_b64_tr_b16 v[24:25], v211 offset:47616
	ds_read_b64_tr_b16 v[26:27], v211 offset:48768
	v_exp_f32_e32 v189, v1
	v_sub_f32_e32 v1, v28, v241
	v_exp_f32_e32 v205, v1
	v_sub_f32_e32 v1, v29, v241
	s_waitcnt lgkmcnt(4)
	v_mfma_f32_32x32x16_bf16 v[34:49], v[112:115], v[50:53], v[34:49]
	v_exp_f32_e32 v167, v1
	v_sub_f32_e32 v1, v30, v241
	v_sub_f32_e32 v19, v31, v241
	v_exp_f32_e32 v1, v1
	v_exp_f32_e32 v19, v19
	v_cvt_pk_bf16_f32 v28, v185, v191
	v_cvt_pk_bf16_f32 v29, v187, v189
	s_waitcnt lgkmcnt(2)
	v_mfma_f32_32x32x16_bf16 v[2:17], v[20:23], v[50:53], v[2:17]
	ds_read_b64_tr_b16 v[22:23], v211 offset:48832
	ds_read_b64_tr_b16 v[20:21], v211 offset:47680
	v_cvt_pk_bf16_f32 v50, v145, v149
	v_cvt_pk_bf16_f32 v51, v153, v157
	v_cvt_pk_bf16_f32 v52, v169, v171
	v_cvt_pk_bf16_f32 v53, v173, v179
	v_cvt_pk_bf16_f32 v30, v205, v167
	v_cvt_pk_bf16_f32 v31, v1, v19
	s_waitcnt lgkmcnt(2)
	v_mfma_f32_32x32x16_bf16 v[34:49], v[24:27], v[50:53], v[34:49]
	ds_read_b64_tr_b16 v[24:25], v211 offset:49920
	ds_read_b64_tr_b16 v[26:27], v211 offset:51072
	v_writelane_b32 v255, s11, 34
	s_waitcnt lgkmcnt(2)
	v_mfma_f32_32x32x16_bf16 v[2:17], v[20:23], v[50:53], v[2:17]
	ds_read_b64_tr_b16 v[22:23], v211 offset:51136
	ds_read_b64_tr_b16 v[20:21], v211 offset:49984
	s_waitcnt vmcnt(3)
	ds_write_b128 v207, v[66:69] offset:15360
	s_waitcnt vmcnt(2)
	ds_write_b128 v207, v[70:73] offset:24576
	s_waitcnt lgkmcnt(0)
	s_barrier
	v_mfma_f32_32x32x16_bf16 v[34:49], v[24:27], v[28:31], v[34:49]
	v_mfma_f32_32x32x16_bf16 v[2:17], v[20:23], v[28:31], v[2:17]
	ds_read_b128 v[20:23], v141 offset:15360
	ds_read_b128 v[24:27], v141 offset:15392
	v_add_f32_e32 v28, 0, v240
	s_waitcnt lgkmcnt(1)
	v_mfma_f32_32x32x16_bf16 v[52:67], v[20:23], v[92:95], 0
	ds_read_b128 v[20:23], v141 offset:15424
	s_waitcnt lgkmcnt(1)
	v_mfma_f32_32x32x16_bf16 v[52:67], v[24:27], v[88:91], v[52:67]
	ds_read_b128 v[24:27], v141 offset:15456
	s_waitcnt lgkmcnt(1)
	v_mfma_f32_32x32x16_bf16 v[52:67], v[20:23], v[84:87], v[52:67]
	v_add_f32_e32 v20, v239, v28
	v_mov_b32_e32 v21, v193
	v_add_f32_e64 v20, v82, v20
	v_add_f32_e64 v21, v83, v21
	v_add_f32_e64 v20, v146, v20
	v_add_f32_e64 v21, v147, v21
	v_pk_add_f32 v[20:21], v[150:151], v[20:21]
	s_waitcnt lgkmcnt(0)
	v_mfma_f32_32x32x16_bf16 v[52:67], v[24:27], v[96:99], v[52:67]
	v_add_f32_e64 v28, v154, v20
	v_add_f32_e64 v29, v155, v21
	ds_read_b128 v[20:23], v238 offset:15360
	v_add_f32_e64 v24, v144, v28
	v_add_f32_e64 v25, v145, v29
	v_pk_add_f32 v[24:25], v[148:149], v[24:25]
	s_nop 0
	v_pk_add_f32 v[24:25], v[152:153], v[24:25]
	s_nop 0
	v_pk_add_f32 v[24:25], v[156:157], v[24:25]
	s_nop 0
	v_pk_add_f32 v[24:25], v[160:161], v[24:25]
	s_nop 0
	v_pk_add_f32 v[28:29], v[162:163], v[24:25]
	ds_read_b128 v[24:27], v238 offset:15392
	s_waitcnt lgkmcnt(1)
	v_mfma_f32_32x32x16_bf16 v[68:83], v[20:23], v[92:95], 0
	v_add_f32_e64 v20, v158, v28
	v_add_f32_e64 v21, v159, v29
	v_add_f32_e64 v20, v164, v20
	v_add_f32_e64 v21, v165, v21
	v_add_f32_e64 v20, v168, v20
	v_add_f32_e64 v21, v169, v21
	v_pk_add_f32 v[20:21], v[170:171], v[20:21]
	s_waitcnt lgkmcnt(0)
	v_mfma_f32_32x32x16_bf16 v[68:83], v[24:27], v[88:91], v[68:83]
	v_add_f32_e64 v20, v172, v20
	v_add_f32_e64 v21, v173, v21
	v_add_f32_e64 v28, v178, v20
	v_add_f32_e64 v29, v179, v21
	ds_read_b128 v[20:23], v238 offset:15424
	v_pk_add_f32 v[24:25], v[174:175], v[28:29]
	v_mov_b32_e32 v175, v193
	v_pk_add_f32 v[24:25], v[176:177], v[24:25]
	s_nop 0
	v_pk_add_f32 v[24:25], v[180:181], v[24:25]
	s_nop 0
	v_pk_add_f32 v[24:25], v[182:183], v[24:25]
	s_nop 0
	v_pk_add_f32 v[24:25], v[184:185], v[24:25]
	s_nop 0
	v_pk_add_f32 v[28:29], v[190:191], v[24:25]
	ds_read_b128 v[24:27], v238 offset:15456
	s_waitcnt lgkmcnt(1)
	v_mfma_f32_32x32x16_bf16 v[68:83], v[20:23], v[84:87], v[68:83]
	v_add_f32_e64 v20, v186, v28
	v_add_f32_e64 v21, v187, v29
	v_add_f32_e64 v20, v188, v20
	v_add_f32_e64 v21, v189, v21
	v_add_f32_e64 v20, v196, v20
	v_add_f32_e64 v21, v197, v21
	v_pk_add_f32 v[20:21], v[198:199], v[20:21]
	s_waitcnt lgkmcnt(0)
	v_mfma_f32_32x32x16_bf16 v[68:83], v[24:27], v[96:99], v[68:83]
	s_nop 0
	v_add_f32_e64 v20, v200, v20
	v_add_f32_e64 v21, v201, v21
	v_add_f32_e64 v20, v202, v20
	v_add_f32_e64 v21, v203, v21
	v_pk_add_f32 v[20:21], v[204:205], v[20:21]
	s_nop 5
	s_nop 1
	v_max_f32_e32 v22, v68, v69
	s_nop 1
	v_max_f32_e32 v23, v70, v71
	v_max3_f32 v22, v22, s23, v23
	s_nop 1
	v_max_f32_e32 v23, v52, v53
	s_nop 0
	v_max_f32_e32 v24, v54, v55
	v_max3_f32 v22, v22, v23, v24
	s_nop 1
	v_max_f32_e32 v23, v72, v73
	s_nop 1
	v_max_f32_e32 v24, v74, v75
	v_max3_f32 v22, v22, v23, v24
	s_nop 1
	v_max_f32_e32 v23, v56, v57
	s_nop 1
	v_max_f32_e32 v24, v58, v59
	v_max3_f32 v22, v22, v23, v24
	s_nop 1
	v_max_f32_e32 v23, v76, v77
	s_nop 1
	v_max_f32_e32 v24, v78, v79
	v_max3_f32 v22, v22, v23, v24
	s_nop 1
	v_max_f32_e32 v23, v60, v61
	s_nop 1
	v_max_f32_e32 v24, v62, v63
	v_max3_f32 v22, v22, v23, v24
	s_nop 1
	v_max_f32_e32 v23, v80, v81
	s_nop 1
	v_max_f32_e32 v24, v82, v83
	v_max3_f32 v22, v22, v23, v24
	s_nop 1
	v_max_f32_e32 v23, v64, v65
	s_nop 1
	v_max_f32_e32 v24, v66, v67
	v_max3_f32 v22, v22, v23, v24
	ds_bpermute_b32 v23, v210, v22
	v_pk_add_f32 v[20:21], v[166:167], v[20:21]
	s_waitcnt lgkmcnt(0)
	v_max3_f32 v125, v241, v22, v23
	v_pk_add_f32 v[0:1], v[0:1], v[20:21]
	v_sub_f32_e32 v22, v58, v125
	v_add_f32_e32 v1, v1, v19
	v_sub_f32_e32 v19, v68, v125
	v_fmac_f32_e32 v1, v0, v18
	v_sub_f32_e32 v18, v55, v125
	v_exp_f32_e32 v127, v19
	v_sub_f32_e32 v19, v69, v125
	v_exp_f32_e32 v124, v18
	v_sub_f32_e32 v18, v72, v125
	v_exp_f32_e32 v129, v19
	v_exp_f32_e32 v126, v18
	v_sub_f32_e32 v18, v73, v125
	v_exp_f32_e32 v128, v18
	v_sub_f32_e32 v18, v74, v125
	v_exp_f32_e32 v154, v18
	v_sub_f32_e32 v18, v75, v125
	v_add_f32_e32 v0, 0, v127
	v_exp_f32_e32 v156, v18
	v_sub_f32_e32 v18, v56, v125
	v_add_f32_e32 v174, v129, v0
	v_sub_f32_e32 v0, v70, v125
	v_exp_f32_e32 v130, v18
	v_sub_f32_e32 v18, v57, v125
	v_exp_f32_e32 v146, v0
	v_sub_f32_e32 v0, v71, v125
	v_exp_f32_e32 v144, v18
	ds_read_b64_tr_b16 v[176:177], v211 offset:24576
	ds_read_b64_tr_b16 v[178:179], v211 offset:25728
	ds_read_b64_tr_b16 v[182:183], v211 offset:25792
	ds_read_b64_tr_b16 v[180:181], v211 offset:24640
	ds_read_b64_tr_b16 v[120:121], v211 offset:26880
	ds_read_b64_tr_b16 v[122:123], v211 offset:28032
	ds_read_b64_tr_b16 v[114:115], v211 offset:28096
	ds_read_b64_tr_b16 v[112:113], v211 offset:26944
	ds_read_b64_tr_b16 v[116:117], v211 offset:29184
	ds_read_b64_tr_b16 v[118:119], v211 offset:30336
	ds_read_b64_tr_b16 v[110:111], v211 offset:30400
	ds_read_b64_tr_b16 v[108:109], v211 offset:29248
	ds_read_b64_tr_b16 v[72:73], v211 offset:31488
	ds_read_b64_tr_b16 v[74:75], v211 offset:32640
	ds_read_b64_tr_b16 v[70:71], v211 offset:32704
	ds_read_b64_tr_b16 v[68:69], v211 offset:31552
	s_waitcnt vmcnt(1)
	ds_write_b128 v207, v[100:103] offset:33792
	s_waitcnt vmcnt(0)
	ds_write_b128 v207, v[104:107] offset:43008
	s_waitcnt lgkmcnt(0)
	s_barrier
	ds_read_b128 v[18:21], v141 offset:33792
	v_exp_f32_e32 v100, v22
	v_sub_f32_e32 v22, v59, v125
	v_exp_f32_e32 v148, v0
	v_sub_f32_e32 v0, v52, v125
	v_exp_f32_e32 v102, v22
	v_sub_f32_e32 v22, v76, v125
	v_exp_f32_e32 v150, v0
	v_sub_f32_e32 v0, v53, v125
	v_exp_f32_e32 v76, v22
	v_sub_f32_e32 v22, v77, v125
	ds_read_b128 v[50:53], v141 offset:33824
	v_exp_f32_e32 v104, v22
	s_waitcnt lgkmcnt(1)
	v_mfma_f32_32x32x16_bf16 v[18:33], v[18:21], v[92:95], 0
	v_exp_f32_e32 v152, v0
	v_sub_f32_e32 v0, v54, v125
	v_sub_f32_e32 v54, v78, v125
	v_exp_f32_e32 v160, v54
	v_sub_f32_e32 v54, v79, v125
	v_exp_f32_e32 v164, v54
	v_sub_f32_e32 v54, v60, v125
	v_exp_f32_e32 v168, v54
	ds_read_b128 v[54:57], v141 offset:33856
	s_waitcnt lgkmcnt(1)
	v_mfma_f32_32x32x16_bf16 v[18:33], v[50:53], v[88:91], v[18:33]
	v_sub_f32_e32 v50, v61, v125
	v_exp_f32_e32 v172, v50
	v_sub_f32_e32 v50, v62, v125
	v_exp_f32_e32 v78, v50
	v_sub_f32_e32 v50, v63, v125
	v_exp_f32_e32 v106, v50
	ds_read_b128 v[50:53], v141 offset:33888
	s_waitcnt lgkmcnt(1)
	v_mfma_f32_32x32x16_bf16 v[18:33], v[54:57], v[84:87], v[18:33]
	v_sub_f32_e32 v54, v80, v125
	v_exp_f32_e32 v80, v54
	v_sub_f32_e32 v54, v81, v125
	v_exp_f32_e32 v158, v54
	v_sub_f32_e32 v54, v82, v125
	v_exp_f32_e32 v82, v54
	ds_read_b128 v[54:57], v238 offset:33792
	ds_read_b128 v[184:187], v238 offset:33824
	s_waitcnt lgkmcnt(2)
	v_mfma_f32_32x32x16_bf16 v[18:33], v[50:53], v[96:99], v[18:33]
	v_sub_f32_e32 v50, v83, v125
	v_exp_f32_e32 v162, v50
	v_sub_f32_e32 v50, v64, v125
	v_exp_f32_e32 v166, v50
	v_sub_f32_e32 v50, v65, v125
	v_exp_f32_e32 v170, v50
	ds_read_b128 v[188:191], v238 offset:33856
	s_waitcnt lgkmcnt(2)
	v_mfma_f32_32x32x16_bf16 v[50:65], v[54:57], v[92:95], 0
	v_sub_f32_e32 v131, v241, v125
	v_exp_f32_e32 v196, v131
	v_sub_f32_e32 v67, v67, v125
	v_exp_f32_e32 v94, v67
	s_nop 0
	v_mul_f32_e32 v92, v1, v196
	v_pk_mul_f32 v[48:49], v[48:49], v[196:197] op_sel_hi:[1,0]
	s_waitcnt lgkmcnt(1)
	v_mfma_f32_32x32x16_bf16 v[50:65], v[184:187], v[88:91], v[50:65]
	ds_read_b128 v[88:91], v238 offset:33888
	v_mul_f32_e64 v46, v46, v196
	v_mul_f32_e64 v47, v47, v196
	v_mul_f32_e64 v44, v44, v196
	v_mul_f32_e64 v45, v45, v196
	v_pk_mul_f32 v[42:43], v[42:43], v[196:197] op_sel_hi:[1,0]
	v_pk_mul_f32 v[40:41], v[40:41], v[196:197] op_sel_hi:[1,0]
	v_pk_mul_f32 v[38:39], v[38:39], v[196:197] op_sel_hi:[1,0]
	v_pk_mul_f32 v[36:37], v[36:37], v[196:197] op_sel_hi:[1,0]
	s_waitcnt lgkmcnt(1)
	v_mfma_f32_32x32x16_bf16 v[50:65], v[188:191], v[84:87], v[50:65]
	v_mul_f32_e64 v34, v34, v196
	v_mul_f32_e64 v35, v35, v196
	v_mul_f32_e64 v16, v16, v196
	v_mul_f32_e64 v17, v17, v196
	v_mul_f32_e64 v14, v14, v196
	v_mul_f32_e64 v15, v15, v196
	v_pk_mul_f32 v[12:13], v[12:13], v[196:197] op_sel_hi:[1,0]
	v_pk_mul_f32 v[10:11], v[10:11], v[196:197] op_sel_hi:[1,0]
	v_pk_mul_f32 v[8:9], v[8:9], v[196:197] op_sel_hi:[1,0]
	v_pk_mul_f32 v[6:7], v[6:7], v[196:197] op_sel_hi:[1,0]
	s_waitcnt lgkmcnt(0)
	v_mfma_f32_32x32x16_bf16 v[50:65], v[88:91], v[96:99], v[50:65]
	v_mul_f32_e64 v4, v4, v196
	v_mul_f32_e64 v5, v5, v196
	v_mul_f32_e64 v2, v2, v196
	v_mul_f32_e64 v3, v3, v196
	v_cvt_pk_bf16_f32 v84, v127, v129
	v_cvt_pk_bf16_f32 v85, v146, v148
	v_cvt_pk_bf16_f32 v86, v126, v128
	v_cvt_pk_bf16_f32 v87, v154, v156
	v_sub_f32_e32 v66, v66, v125
	s_nop 2
	s_nop 1
	v_max_f32_e32 v1, v50, v51
	s_nop 1
	v_max_f32_e32 v67, v52, v53
	v_max3_f32 v1, v1, s23, v67
	s_nop 1
	v_max_f32_e32 v67, v18, v19
	s_nop 0
	v_max_f32_e32 v77, v20, v21
	v_max3_f32 v1, v1, v67, v77
	s_nop 1
	v_max_f32_e32 v67, v54, v55
	s_nop 1
	v_max_f32_e32 v77, v56, v57
	v_max3_f32 v1, v1, v67, v77
	s_nop 1
	v_max_f32_e32 v67, v22, v23
	s_nop 1
	v_max_f32_e32 v77, v24, v25
	v_max3_f32 v1, v1, v67, v77
	s_nop 1
	v_max_f32_e32 v67, v58, v59
	s_nop 1
	v_max_f32_e32 v77, v60, v61
	v_max3_f32 v1, v1, v67, v77
	s_nop 1
	v_max_f32_e32 v67, v26, v27
	s_nop 1
	v_max_f32_e32 v77, v28, v29
	v_max3_f32 v1, v1, v67, v77
	s_nop 1
	v_max_f32_e32 v67, v62, v63
	s_nop 1
	v_max_f32_e32 v77, v64, v65
	v_max3_f32 v1, v1, v67, v77
	s_nop 1
	v_max_f32_e32 v67, v30, v31
	s_nop 1
	v_max_f32_e32 v77, v32, v33
	v_max3_f32 v1, v1, v67, v77
	ds_bpermute_b32 v67, v210, v1
	v_mfma_f32_32x32x16_bf16 v[34:49], v[176:179], v[84:87], v[34:49]
	v_exp_f32_e32 v0, v0
	v_exp_f32_e32 v66, v66
	v_mov_b32_e32 v141, v193
	s_waitcnt lgkmcnt(0)
	v_max3_f32 v96, v125, v1, v67
	v_sub_f32_e32 v1, v50, v96
	v_exp_f32_e32 v147, v1
	v_sub_f32_e32 v1, v51, v96
	v_mfma_f32_32x32x16_bf16 v[2:17], v[180:183], v[84:87], v[2:17]
	v_exp_f32_e32 v149, v1
	v_sub_f32_e32 v1, v52, v96
	v_exp_f32_e32 v151, v1
	v_sub_f32_e32 v1, v53, v96
	v_exp_f32_e32 v153, v1
	v_sub_f32_e32 v1, v18, v96
	v_sub_f32_e32 v18, v19, v96
	v_sub_f32_e32 v67, v125, v96
	v_exp_f32_e32 v125, v18
	v_sub_f32_e32 v18, v20, v96
	v_exp_f32_e32 v127, v18
	v_sub_f32_e32 v18, v21, v96
	v_exp_f32_e32 v129, v18
	v_sub_f32_e32 v18, v54, v96
	v_exp_f32_e32 v1, v1
	v_exp_f32_e32 v155, v18
	v_pk_add_f32 v[18:19], v[146:147], v[174:175]
	v_cvt_pk_bf16_f32 v50, v76, v104
	v_cvt_pk_bf16_f32 v51, v160, v164
	v_cvt_pk_bf16_f32 v52, v80, v158
	v_cvt_pk_bf16_f32 v53, v82, v162
	v_pk_add_f32 v[18:19], v[148:149], v[18:19]
	v_cvt_pk_bf16_f32 v21, v0, v124
	v_mfma_f32_32x32x16_bf16 v[34:49], v[120:123], v[50:53], v[34:49]
	v_add_f32_e64 v18, v150, v18
	v_add_f32_e64 v19, v151, v19
	v_cvt_pk_bf16_f32 v20, v150, v152
	v_add_f32_e64 v18, v152, v18
	v_add_f32_e64 v19, v153, v19
	v_pk_add_f32 v[18:19], v[0:1], v[18:19]
	v_sub_f32_e32 v0, v55, v96
	v_exp_f32_e32 v157, v0
	v_mfma_f32_32x32x16_bf16 v[2:17], v[112:115], v[50:53], v[2:17]
	v_sub_f32_e32 v0, v56, v96
	v_exp_f32_e32 v131, v0
	v_sub_f32_e32 v0, v57, v96
	v_exp_f32_e32 v145, v0
	v_sub_f32_e32 v0, v22, v96
	v_exp_f32_e32 v101, v0
	v_sub_f32_e32 v0, v23, v96
	v_cvt_pk_bf16_f32 v22, v130, v144
	v_cvt_pk_bf16_f32 v23, v100, v102
	v_exp_f32_e32 v103, v0
	v_sub_f32_e32 v0, v24, v96
	v_mfma_f32_32x32x16_bf16 v[34:49], v[116:119], v[20:23], v[34:49]
	v_exp_f32_e32 v77, v0
	v_sub_f32_e32 v0, v25, v96
	v_exp_f32_e32 v105, v0
	v_sub_f32_e32 v0, v58, v96
	v_exp_f32_e32 v161, v0
	v_sub_f32_e32 v0, v59, v96
	v_exp_f32_e32 v165, v0
	v_mfma_f32_32x32x16_bf16 v[2:17], v[108:111], v[20:23], v[2:17]
	v_sub_f32_e32 v0, v60, v96
	v_exp_f32_e32 v169, v0
	v_sub_f32_e32 v0, v61, v96
	v_exp_f32_e32 v173, v0
	v_sub_f32_e32 v0, v26, v96
	v_cvt_pk_bf16_f32 v24, v168, v172
	v_exp_f32_e32 v79, v0
	v_sub_f32_e32 v0, v27, v96
	v_cvt_pk_bf16_f32 v25, v78, v106
	v_cvt_pk_bf16_f32 v26, v166, v170
	v_cvt_pk_bf16_f32 v27, v66, v94
	v_exp_f32_e32 v107, v0
	v_sub_f32_e32 v0, v28, v96
	v_mfma_f32_32x32x16_bf16 v[34:49], v[72:75], v[24:27], v[34:49]
	v_exp_f32_e32 v81, v0
	v_sub_f32_e32 v0, v29, v96
	v_pk_add_f32 v[18:19], v[124:125], v[18:19]
	v_exp_f32_e32 v159, v0
	v_sub_f32_e32 v0, v62, v96
	v_pk_add_f32 v[18:19], v[126:127], v[18:19]
	v_exp_f32_e32 v83, v0
	v_mfma_f32_32x32x16_bf16 v[2:17], v[68:71], v[24:27], v[2:17]
	v_sub_f32_e32 v0, v63, v96
	v_sub_f32_e32 v20, v64, v96
	v_add_f32_e64 v18, v128, v18
	v_add_f32_e64 v19, v129, v19
	v_exp_f32_e32 v163, v0
	v_exp_f32_e32 v0, v67
	v_exp_f32_e32 v167, v20
	ds_read_b64_tr_b16 v[20:21], v211 offset:43008
	ds_read_b64_tr_b16 v[22:23], v211 offset:44160
	ds_read_b64_tr_b16 v[26:27], v211 offset:44224
	ds_read_b64_tr_b16 v[24:25], v211 offset:43072
	v_lshlrev_b64 v[28:29], 11, v[142:143]
	v_pk_add_f32 v[18:19], v[154:155], v[18:19]
	v_lshl_add_u64 v[28:29], s[0:1], 0, v[28:29]
	v_pk_add_f32 v[18:19], v[156:157], v[18:19]
	v_lshl_add_u64 v[28:29], v[28:29], 0, s[18:19]
	v_pk_add_f32 v[18:19], v[130:131], v[18:19]
	v_lshl_add_u64 v[28:29], v[28:29], 0, v[140:141]
	v_pk_add_f32 v[18:19], v[144:145], v[18:19]
	v_pk_mul_f32 v[48:49], v[48:49], v[0:1] op_sel_hi:[1,0]
	v_pk_mul_f32 v[46:47], v[46:47], v[0:1] op_sel_hi:[1,0]
	v_pk_mul_f32 v[44:45], v[44:45], v[0:1] op_sel_hi:[1,0]
	v_pk_mul_f32 v[42:43], v[42:43], v[0:1] op_sel_hi:[1,0]
	v_pk_mul_f32 v[40:41], v[40:41], v[0:1] op_sel_hi:[1,0]
	v_pk_mul_f32 v[38:39], v[38:39], v[0:1] op_sel_hi:[1,0]
	v_pk_mul_f32 v[36:37], v[36:37], v[0:1] op_sel_hi:[1,0]
	v_pk_mul_f32 v[34:35], v[34:35], v[0:1] op_sel_hi:[1,0]
	v_pk_mul_f32 v[16:17], v[16:17], v[0:1] op_sel_hi:[1,0]
	v_cvt_pk_bf16_f32 v50, v147, v149
	v_cvt_pk_bf16_f32 v51, v151, v153
	v_cvt_pk_bf16_f32 v52, v155, v157
	ds_read_b64_tr_b16 v[54:55], v211 offset:45312
	ds_read_b64_tr_b16 v[56:57], v211 offset:46464
	ds_read_b64_tr_b16 v[60:61], v211 offset:46528
	ds_read_b64_tr_b16 v[58:59], v211 offset:45376
	ds_read_b64_tr_b16 v[68:69], v211 offset:47616
	ds_read_b64_tr_b16 v[70:71], v211 offset:48768
	ds_read_b64_tr_b16 v[74:75], v211 offset:48832
	ds_read_b64_tr_b16 v[72:73], v211 offset:47680
	ds_read_b64_tr_b16 v[84:85], v211 offset:49920
	ds_read_b64_tr_b16 v[86:87], v211 offset:51072
	ds_read_b64_tr_b16 v[90:91], v211 offset:51136
	ds_read_b64_tr_b16 v[88:89], v211 offset:49984
	s_waitcnt lgkmcnt(0)
	s_barrier
	v_mov_b64_e32 v[62:63], v[224:225]
	v_cvt_pk_bf16_f32 v53, v131, v145
	v_pk_mul_f32 v[14:15], v[14:15], v[0:1] op_sel_hi:[1,0]
	v_pk_mul_f32 v[12:13], v[12:13], v[0:1] op_sel_hi:[1,0]
	v_pk_mul_f32 v[10:11], v[10:11], v[0:1] op_sel_hi:[1,0]
	v_pk_mul_f32 v[8:9], v[8:9], v[0:1] op_sel_hi:[1,0]
	v_pk_mul_f32 v[6:7], v[6:7], v[0:1] op_sel_hi:[1,0]
	v_pk_mul_f32 v[4:5], v[4:5], v[0:1] op_sel_hi:[1,0]
	v_pk_mul_f32 v[2:3], v[2:3], v[0:1] op_sel_hi:[1,0]
	v_pk_add_f32 v[18:19], v[100:101], v[18:19]
	v_mfma_f32_32x32x16_bf16 v[34:49], v[20:23], v[50:53], v[34:49]
	v_add_f32_e64 v18, v102, v18
	v_add_f32_e64 v19, v103, v19
	v_sub_f32_e32 v20, v65, v96
	v_add_f32_e64 v18, v76, v18
	v_add_f32_e64 v19, v77, v19
	v_exp_f32_e32 v171, v20
	v_pk_add_f32 v[18:19], v[104:105], v[18:19]
	v_cvt_pk_bf16_f32 v20, v161, v165
	v_pk_add_f32 v[18:19], v[160:161], v[18:19]
	v_mfma_f32_32x32x16_bf16 v[2:17], v[24:27], v[50:53], v[2:17]
	v_mov_b64_e32 v[24:25], v[226:227]
	v_add_f32_e64 v18, v164, v18
	v_add_f32_e64 v19, v165, v19
	v_sub_f32_e32 v26, v30, v96
	v_add_f32_e64 v18, v168, v18
	v_add_f32_e64 v19, v169, v19
	v_cvt_pk_bf16_f32 v21, v169, v173
	v_pk_add_f32 v[18:19], v[172:173], v[18:19]
	v_cvt_pk_bf16_f32 v22, v83, v163
	v_cvt_pk_bf16_f32 v23, v167, v171
	v_exp_f32_e32 v67, v26
	v_mov_b64_e32 v[26:27], v[246:247]
	v_mfma_f32_32x32x16_bf16 v[34:49], v[54:57], v[20:23], v[34:49]
	v_sub_f32_e32 v30, v31, v96
	v_exp_f32_e32 v95, v30
	v_sub_f32_e32 v30, v32, v96
	v_exp_f32_e32 v93, v30
	v_sub_f32_e32 v30, v33, v96
	v_exp_f32_e32 v50, v30
	v_mov_b64_e32 v[30:31], v[248:249]
	v_mfma_f32_32x32x16_bf16 v[2:17], v[58:61], v[20:23], v[2:17]
	v_add_f32_e64 v22, v78, v18
	v_add_f32_e64 v23, v79, v19
	v_cvt_pk_bf16_f32 v18, v1, v125
	v_add_f32_e64 v22, v106, v22
	v_add_f32_e64 v23, v107, v23
	v_cvt_pk_bf16_f32 v19, v127, v129
	v_pk_add_f32 v[22:23], v[80:81], v[22:23]
	v_cvt_pk_bf16_f32 v20, v101, v103
	v_pk_add_f32 v[22:23], v[158:159], v[22:23]
	v_cvt_pk_bf16_f32 v21, v77, v105
	v_pk_add_f32 v[22:23], v[82:83], v[22:23]
	v_mov_b64_e32 v[32:33], v[214:215]
	v_pk_add_f32 v[22:23], v[162:163], v[22:23]
	v_mfma_f32_32x32x16_bf16 v[34:49], v[68:71], v[18:21], v[34:49]
	v_add_f32_e64 v22, v166, v22
	v_add_f32_e64 v23, v167, v23
	v_add_f32_e64 v22, v170, v22
	v_add_f32_e64 v23, v171, v23
	v_mfma_f32_32x32x16_bf16 v[2:17], v[72:75], v[18:21], v[2:17]
	v_add_f32_e64 v18, v66, v22
	v_add_f32_e64 v19, v67, v23
	v_cvt_pk_bf16_f32 v20, v67, v95
	v_add_f32_e64 v18, v94, v18
	v_add_f32_e64 v19, v95, v19
	v_cvt_pk_bf16_f32 v21, v93, v50
	v_pk_add_f32 v[22:23], v[92:93], v[18:19]
	v_cvt_pk_bf16_f32 v18, v79, v107
	v_add_f32_e32 v23, v23, v50
	v_fmac_f32_e32 v23, v22, v0
	v_mov_b64_e32 v[0:1], v[216:217]
	v_cvt_pk_bf16_f32 v19, v81, v159
	ds_bpermute_b32 v22, v210, v23
	s_waitcnt lgkmcnt(0)
	v_add_f32_e32 v22, v23, v22
	v_mfma_f32_32x32x16_bf16 v[34:49], v[84:87], v[18:21], v[34:49]
	v_div_scale_f32 v23, s[10:11], v22, v22, 1.0
	v_rcp_f32_e32 v50, v23
	v_readlane_b32 s10, v254, 56
	v_readlane_b32 s11, v254, 57
	v_fma_f32 v51, -v23, v50, 1.0
	v_mfma_f32_32x32x16_bf16 v[2:17], v[88:91], v[18:21], v[2:17]
	v_mov_b64_e32 v[18:19], v[230:231]
	v_mov_b64_e32 v[20:21], v[232:233]
	v_fmac_f32_e32 v50, v51, v50
	v_div_scale_f32 v51, vcc, 1.0, v22, 1.0
	v_mul_f32_e32 v52, v51, v50
	v_fma_f32 v53, -v23, v52, v51
	v_fmac_f32_e32 v52, v53, v50
	v_fma_f32 v23, -v23, v52, v51
	v_div_fmas_f32 v23, v23, v50, v52
	v_div_fixup_f32 v22, v23, v22, 1.0
	v_pk_mul_f32 v[34:35], v[34:35], v[22:23] op_sel_hi:[1,0]
	s_waitcnt vmcnt(7)
	v_lshlrev_b32_e32 v50, 16, v62
	v_and_b32_e32 v51, 0xffff0000, v62
	v_pk_mul_f32 v[34:35], v[34:35], v[50:51]
	v_pk_mul_f32 v[36:37], v[36:37], v[22:23] op_sel_hi:[1,0]
	v_lshlrev_b32_e32 v50, 16, v63
	v_and_b32_e32 v51, 0xffff0000, v63
	v_pk_mul_f32 v[36:37], v[36:37], v[50:51]
	v_cvt_pk_bf16_f32 v34, v34, v35
	v_cvt_pk_bf16_f32 v35, v36, v37
	global_store_dwordx2 v[28:29], v[34:35], off
	v_pk_mul_f32 v[34:35], v[38:39], v[22:23] op_sel_hi:[1,0]
	s_waitcnt vmcnt(7)
	v_lshlrev_b32_e32 v36, 16, v24
	v_and_b32_e32 v37, 0xffff0000, v24
	v_pk_mul_f32 v[34:35], v[34:35], v[36:37]
	v_lshlrev_b32_e32 v36, 16, v25
	v_cvt_pk_bf16_f32 v24, v34, v35
	v_pk_mul_f32 v[34:35], v[40:41], v[22:23] op_sel_hi:[1,0]
	v_and_b32_e32 v37, 0xffff0000, v25
	v_pk_mul_f32 v[34:35], v[34:35], v[36:37]
	v_pk_mul_f32 v[2:3], v[2:3], v[22:23] op_sel_hi:[1,0]
	v_cvt_pk_bf16_f32 v25, v34, v35
	global_store_dwordx2 v[28:29], v[24:25], off offset:16
	v_pk_mul_f32 v[24:25], v[42:43], v[22:23] op_sel_hi:[1,0]
	s_waitcnt vmcnt(7)
	v_lshlrev_b32_e32 v34, 16, v26
	v_and_b32_e32 v35, 0xffff0000, v26
	v_pk_mul_f32 v[24:25], v[24:25], v[34:35]
	v_pk_mul_f32 v[34:35], v[44:45], v[22:23] op_sel_hi:[1,0]
	v_lshlrev_b32_e32 v26, 16, v27
	v_and_b32_e32 v27, 0xffff0000, v27
	v_pk_mul_f32 v[26:27], v[34:35], v[26:27]
	v_cvt_pk_bf16_f32 v24, v24, v25
	v_cvt_pk_bf16_f32 v25, v26, v27
	global_store_dwordx2 v[28:29], v[24:25], off offset:32
	v_pk_mul_f32 v[24:25], v[46:47], v[22:23] op_sel_hi:[1,0]
	s_waitcnt vmcnt(7)
	v_lshlrev_b32_e32 v26, 16, v30
	v_and_b32_e32 v27, 0xffff0000, v30
	v_pk_mul_f32 v[24:25], v[24:25], v[26:27]
	v_pk_mul_f32 v[26:27], v[48:49], v[22:23] op_sel_hi:[1,0]
	v_lshlrev_b32_e32 v30, 16, v31
	v_and_b32_e32 v31, 0xffff0000, v31
	v_pk_mul_f32 v[26:27], v[26:27], v[30:31]
	v_cvt_pk_bf16_f32 v24, v24, v25
	v_cvt_pk_bf16_f32 v25, v26, v27
	global_store_dwordx2 v[28:29], v[24:25], off offset:48
	s_waitcnt vmcnt(7)
	v_lshlrev_b32_e32 v24, 16, v32
	v_and_b32_e32 v25, 0xffff0000, v32
	v_pk_mul_f32 v[2:3], v[2:3], v[24:25]
	v_pk_mul_f32 v[4:5], v[4:5], v[22:23] op_sel_hi:[1,0]
	v_lshlrev_b32_e32 v24, 16, v33
	v_and_b32_e32 v25, 0xffff0000, v33
	v_pk_mul_f32 v[4:5], v[4:5], v[24:25]
	v_cvt_pk_bf16_f32 v2, v2, v3
	v_cvt_pk_bf16_f32 v3, v4, v5
	global_store_dwordx2 v[28:29], v[2:3], off offset:64
	v_pk_mul_f32 v[2:3], v[6:7], v[22:23] op_sel_hi:[1,0]
	s_waitcnt vmcnt(7)
	v_lshlrev_b32_e32 v4, 16, v0
	v_and_b32_e32 v5, 0xffff0000, v0
	v_pk_mul_f32 v[2:3], v[2:3], v[4:5]
	v_lshlrev_b32_e32 v4, 16, v1
	v_cvt_pk_bf16_f32 v0, v2, v3
	v_pk_mul_f32 v[2:3], v[8:9], v[22:23] op_sel_hi:[1,0]
	v_and_b32_e32 v5, 0xffff0000, v1
	v_pk_mul_f32 v[2:3], v[2:3], v[4:5]
	s_andn2_b64 vcc, exec, s[10:11]
	v_cvt_pk_bf16_f32 v1, v2, v3
	global_store_dwordx2 v[28:29], v[0:1], off offset:80
	v_pk_mul_f32 v[0:1], v[10:11], v[22:23] op_sel_hi:[1,0]
	s_waitcnt vmcnt(7)
	v_lshlrev_b32_e32 v2, 16, v18
	v_and_b32_e32 v3, 0xffff0000, v18
	v_pk_mul_f32 v[0:1], v[0:1], v[2:3]
	v_pk_mul_f32 v[2:3], v[12:13], v[22:23] op_sel_hi:[1,0]
	v_lshlrev_b32_e32 v4, 16, v19
	v_and_b32_e32 v5, 0xffff0000, v19
	v_pk_mul_f32 v[2:3], v[2:3], v[4:5]
	v_cvt_pk_bf16_f32 v0, v0, v1
	v_cvt_pk_bf16_f32 v1, v2, v3
	global_store_dwordx2 v[28:29], v[0:1], off offset:96
	v_pk_mul_f32 v[0:1], v[14:15], v[22:23] op_sel_hi:[1,0]
	s_waitcnt vmcnt(7)
	v_lshlrev_b32_e32 v2, 16, v20
	v_and_b32_e32 v3, 0xffff0000, v20
	v_pk_mul_f32 v[0:1], v[0:1], v[2:3]
	v_pk_mul_f32 v[2:3], v[16:17], v[22:23] op_sel_hi:[1,0]
	v_lshlrev_b32_e32 v4, 16, v21
	v_and_b32_e32 v5, 0xffff0000, v21
	v_pk_mul_f32 v[2:3], v[2:3], v[4:5]
	v_cvt_pk_bf16_f32 v0, v0, v1
	v_cvt_pk_bf16_f32 v1, v2, v3
	global_store_dwordx2 v[28:29], v[0:1], off offset:112
	s_cbranch_vccnz .LBB0_1405
	v_readlane_b32 s5, v254, 58
	s_add_i32 s4, s4, s5
	v_lshlrev_b64 v[0:1], 9, v[132:133]
	v_or_b32_e32 v132, s4, v135
	v_readlane_b32 s10, v255, 21
	v_ashrrev_i32_e32 v133, 31, v132
	v_readlane_b32 s16, v255, 35
	s_add_u32 s4, s50, s10
	v_lshlrev_b64 v[2:3], 10, v[132:133]
	v_readlane_b32 s17, v255, 36
	s_addc_u32 s5, s51, 0
	v_lshl_add_u64 v[2:3], s[20:21], 0, v[2:3]
	s_mov_b32 s17, s13
	v_lshlrev_b64 v[204:205], 11, v[132:133]
	v_lshlrev_b32_e32 v224, 1, v206
	v_mov_b32_e32 v225, 0
	v_lshl_add_u64 v[204:205], s[0:1], 0, v[204:205]
	v_lshl_add_u64 v[204:205], v[204:205], 0, s[16:17]
	v_lshl_add_u64 v[204:205], v[204:205], 0, v[224:225]
	global_load_dwordx2 v[238:239], v[204:205], off
	global_load_dwordx2 v[240:241], v[204:205], off offset:16
	global_load_dwordx2 v[242:243], v[204:205], off offset:32
	global_load_dwordx2 v[244:245], v[204:205], off offset:48
	global_load_dwordx2 v[246:247], v[204:205], off offset:64
	global_load_dwordx2 v[248:249], v[204:205], off offset:80
	global_load_dwordx2 v[224:225], v[204:205], off offset:96
	global_load_dwordx2 v[226:227], v[204:205], off offset:112
	s_add_u32 s10, s36, s10
	v_lshl_add_u64 v[2:3], v[2:3], 0, s[16:17]
	s_addc_u32 s11, s37, 0
	v_lshlrev_b64 v[10:11], 1, v[0:1]
	v_lshl_add_u64 v[8:9], v[2:3], 0, v[192:193]
	v_lshl_add_u64 v[0:1], s[4:5], 0, v[10:11]
	v_lshlrev_b32_e32 v192, 1, v134
	v_lshl_add_u64 v[2:3], s[10:11], 0, v[10:11]
	v_lshl_add_u64 v[0:1], v[0:1], 0, v[192:193]
	v_lshl_add_u64 v[4:5], v[2:3], 0, v[192:193]
	global_load_dwordx4 v[0:3], v[0:1], off
	s_nop 0
	global_load_dwordx4 v[4:7], v[4:5], off
	s_nop 0
	global_load_dwordx4 v[92:95], v[8:9], off
	global_load_dwordx4 v[88:91], v[8:9], off offset:32
	global_load_dwordx4 v[84:87], v[8:9], off offset:64
	global_load_dwordx4 v[96:99], v[8:9], off offset:96
	v_readlane_b32 s10, v255, 22
	s_add_u32 s4, s50, s10
	s_addc_u32 s5, s51, 0
	s_add_u32 s10, s36, s10
	v_mul_u32_u24_e32 v12, 0x90, v209
	v_lshl_add_u64 v[8:9], s[4:5], 0, v[10:11]
	s_addc_u32 s11, s37, 0
	v_add_u32_e32 v196, v237, v12
	v_lshl_add_u64 v[8:9], v[8:9], 0, v[192:193]
	v_lshl_add_u64 v[12:13], s[10:11], 0, v[10:11]
	v_lshl_add_u64 v[12:13], v[12:13], 0, v[192:193]
	global_load_dwordx4 v[16:19], v[8:9], off
	global_load_dwordx4 v[38:41], v[12:13], off
	v_readlane_b32 s10, v255, 23
	s_add_u32 s4, s50, s10
	s_addc_u32 s5, s51, 0
	s_add_u32 s10, s36, s10
	v_lshl_add_u64 v[8:9], s[4:5], 0, v[10:11]
	s_addc_u32 s11, s37, 0
	v_lshl_add_u64 v[8:9], v[8:9], 0, v[192:193]
	v_lshl_add_u64 v[10:11], s[10:11], 0, v[10:11]
	v_lshl_add_u64 v[10:11], v[10:11], 0, v[192:193]
	global_load_dwordx4 v[66:69], v[8:9], off
	global_load_dwordx4 v[70:73], v[10:11], off
	s_barrier
	v_add_u32_e32 v197, v237, v208
	v_readlane_b32 s4, v255, 37
	v_readlane_b32 s5, v255, 38
	s_mov_b32 s5, s13
	s_mov_b32 s10, s4
	v_writelane_b32 v255, s10, 37
	s_waitcnt vmcnt(9)
	ds_write_b128 v207, v[0:3] offset:15360
	s_waitcnt vmcnt(8)
	ds_write_b128 v207, v[4:7] offset:24576
	s_waitcnt lgkmcnt(0)
	s_barrier
	ds_read_b128 v[0:3], v196 offset:15360
	ds_read_b128 v[42:45], v196 offset:15392
	s_waitcnt vmcnt(7) lgkmcnt(1)
	v_mfma_f32_32x32x16_bf16 v[0:15], v[0:3], v[92:95], 0
	ds_read_b128 v[20:23], v197 offset:15360
	ds_read_b128 v[46:49], v197 offset:15392
	v_writelane_b32 v255, s11, 38
	s_waitcnt lgkmcnt(1)
	v_mfma_f32_32x32x16_bf16 v[22:37], v[20:23], v[92:95], 0
	s_waitcnt vmcnt(6)
	v_mfma_f32_32x32x16_bf16 v[0:15], v[42:45], v[88:91], v[0:15]
	s_waitcnt lgkmcnt(0)
	v_mfma_f32_32x32x16_bf16 v[22:37], v[46:49], v[88:91], v[22:37]
	ds_read_b128 v[42:45], v196 offset:15424
	ds_read_b128 v[46:49], v196 offset:15456
	s_waitcnt vmcnt(5) lgkmcnt(1)
	v_mfma_f32_32x32x16_bf16 v[0:15], v[42:45], v[84:87], v[0:15]
	ds_read_b128 v[42:45], v197 offset:15424
	ds_read_b128 v[50:53], v197 offset:15456
	s_waitcnt lgkmcnt(1)
	v_mfma_f32_32x32x16_bf16 v[22:37], v[42:45], v[84:87], v[22:37]
	s_waitcnt vmcnt(4) lgkmcnt(0)
	v_mfma_f32_32x32x16_bf16 v[22:37], v[50:53], v[96:99], v[22:37]
	v_mfma_f32_32x32x16_bf16 v[0:15], v[46:49], v[96:99], v[0:15]
	s_nop 10
	s_nop 0
	s_nop 0
	s_nop 0
	s_nop 0
	v_max_f32_e32 v20, v22, v23
	v_max_f32_e32 v21, v24, v25
	s_nop 0
	s_nop 0
	s_nop 0
	s_nop 0
	s_nop 0
	s_nop 0
	s_nop 0
	s_nop 0
	v_max_f32_e32 v42, v0, v1
	v_max_f32_e32 v43, v2, v3
	v_max3_f32 v20, v20, s23, v21
	s_nop 0
	s_nop 0
	s_nop 0
	s_nop 0
	v_max_f32_e32 v44, v26, v27
	v_max_f32_e32 v45, v28, v29
	v_max3_f32 v20, v20, v42, v43
	v_max_f32_e32 v56, v31, v31
	v_max_f32_e32 v57, v30, v30
	v_max_f32_e32 v58, v33, v33
	v_max_f32_e32 v59, v32, v32
	v_max_f32_e32 v46, v4, v5
	v_max_f32_e32 v47, v6, v7
	v_max3_f32 v20, v20, v44, v45
	v_max_f32_e32 v60, v9, v9
	v_max_f32_e32 v61, v8, v8
	v_max_f32_e32 v62, v11, v11
	v_max_f32_e32 v63, v10, v10
	v_max_f32_e32 v48, v57, v56
	v_max_f32_e32 v49, v59, v58
	v_max3_f32 v20, v20, v46, v47
	v_max_f32_e32 v64, v35, v35
	v_max_f32_e32 v65, v34, v34
	s_nop 0
	s_nop 0
	v_max_f32_e32 v50, v61, v60
	v_max_f32_e32 v51, v63, v62
	v_max3_f32 v20, v20, v48, v49
	s_nop 0
	s_nop 0
	s_nop 0
	s_nop 0
	v_max_f32_e32 v52, v65, v64
	v_max_f32_e32 v53, v36, v37
	v_max3_f32 v20, v20, v50, v51
	v_max_f32_e32 v54, v12, v13
	v_max_f32_e32 v55, v14, v15
	v_max3_f32 v20, v20, v52, v53
	v_max3_f32 v44, v20, v54, v55
	ds_bpermute_b32 v45, v210, v44
	v_lshl_add_u64 v[42:43], v[136:137], 0, s[4:5]
	v_lshl_add_u64 v[20:21], v[138:139], 0, s[4:5]
	global_load_dwordx4 v[100:103], v[42:43], off
	global_load_dwordx4 v[104:107], v[20:21], off
	ds_read_b64_tr_b16 v[128:129], v211 offset:24576
	ds_read_b64_tr_b16 v[130:131], v211 offset:25728
	ds_read_b64_tr_b16 v[126:127], v211 offset:25792
	ds_read_b64_tr_b16 v[124:125], v211 offset:24640
	ds_read_b64_tr_b16 v[120:121], v211 offset:26880
	ds_read_b64_tr_b16 v[122:123], v211 offset:28032
	ds_read_b64_tr_b16 v[118:119], v211 offset:28096
	ds_read_b64_tr_b16 v[116:117], v211 offset:26944
	ds_read_b64_tr_b16 v[112:113], v211 offset:29184
	ds_read_b64_tr_b16 v[114:115], v211 offset:30336
	ds_read_b64_tr_b16 v[110:111], v211 offset:30400
	ds_read_b64_tr_b16 v[108:109], v211 offset:29248
	ds_read_b64_tr_b16 v[78:79], v211 offset:31488
	ds_read_b64_tr_b16 v[80:81], v211 offset:32640
	ds_read_b64_tr_b16 v[76:77], v211 offset:32704
	ds_read_b64_tr_b16 v[74:75], v211 offset:31552
	s_waitcnt lgkmcnt(14)
	v_max3_f32 v52, v44, v45, s23
	v_sub_f32_e32 v0, v0, v52
	v_exp_f32_e32 v140, v0
	v_sub_f32_e32 v0, v2, v52
	v_exp_f32_e32 v82, v0
	v_sub_f32_e32 v0, v3, v52
	v_exp_f32_e32 v134, v0
	v_sub_f32_e32 v0, v26, v52
	v_exp_f32_e32 v136, v0
	v_sub_f32_e32 v0, v27, v52
	v_exp_f32_e32 v146, v0
	v_sub_f32_e32 v0, v28, v52
	v_exp_f32_e32 v150, v0
	v_sub_f32_e32 v0, v29, v52
	v_exp_f32_e32 v152, v0
	v_sub_f32_e32 v0, v4, v52
	v_sub_f32_e32 v1, v1, v52
	v_exp_f32_e32 v148, v0
	v_sub_f32_e32 v0, v5, v52
	v_exp_f32_e32 v138, v1
	v_exp_f32_e32 v154, v0
	s_waitcnt vmcnt(5)
	ds_write_b128 v207, v[16:19] offset:33792
	s_waitcnt vmcnt(4)
	ds_write_b128 v207, v[38:41] offset:43008
	s_waitcnt lgkmcnt(0)
	s_barrier
	ds_read_b128 v[0:3], v196 offset:33792
	v_sub_f32_e32 v4, v6, v52
	v_exp_f32_e32 v158, v4
	v_sub_f32_e32 v4, v7, v52
	v_exp_f32_e32 v160, v4
	v_sub_f32_e32 v4, v30, v52
	v_sub_f32_e32 v20, v22, v52
	v_sub_f32_e32 v21, v23, v52
	v_sub_f32_e32 v22, v24, v52
	v_sub_f32_e32 v23, v25, v52
	v_exp_f32_e32 v162, v4
	ds_read_b128 v[4:7], v196 offset:33824
	v_exp_f32_e32 v192, v20
	v_exp_f32_e32 v198, v21
	v_exp_f32_e32 v144, v22
	v_exp_f32_e32 v142, v23
	v_sub_f32_e32 v38, v31, v52
	s_waitcnt lgkmcnt(1)
	v_mfma_f32_32x32x16_bf16 v[16:31], v[0:3], v[92:95], 0
	v_sub_f32_e32 v0, v32, v52
	v_exp_f32_e32 v164, v0
	v_sub_f32_e32 v0, v33, v52
	v_exp_f32_e32 v166, v0
	ds_read_b128 v[0:3], v196 offset:33856
	v_sub_f32_e32 v8, v8, v52
	v_exp_f32_e32 v170, v8
	s_waitcnt lgkmcnt(1)
	v_mfma_f32_32x32x16_bf16 v[16:31], v[4:7], v[88:91], v[16:31]
	v_sub_f32_e32 v4, v9, v52
	v_exp_f32_e32 v172, v4
	v_sub_f32_e32 v4, v10, v52
	v_exp_f32_e32 v174, v4
	ds_read_b128 v[4:7], v196 offset:33888
	v_sub_f32_e32 v8, v11, v52
	v_exp_f32_e32 v168, v38
	s_waitcnt lgkmcnt(1)
	v_mfma_f32_32x32x16_bf16 v[16:31], v[0:3], v[84:87], v[16:31]
	v_sub_f32_e32 v0, v34, v52
	v_exp_f32_e32 v176, v0
	v_sub_f32_e32 v0, v35, v52
	v_exp_f32_e32 v178, v0
	ds_read_b128 v[0:3], v197 offset:33792
	v_exp_f32_e32 v180, v8
	v_sub_f32_e32 v8, v36, v52
	s_waitcnt lgkmcnt(1)
	v_mfma_f32_32x32x16_bf16 v[16:31], v[4:7], v[96:99], v[16:31]
	v_sub_f32_e32 v4, v37, v52
	v_exp_f32_e32 v184, v4
	v_sub_f32_e32 v4, v12, v52
	v_exp_f32_e32 v186, v4
	ds_read_b128 v[4:7], v197 offset:33824
	v_exp_f32_e32 v182, v8
	v_sub_f32_e32 v8, v13, v52
	s_waitcnt lgkmcnt(1)
	v_mfma_f32_32x32x16_bf16 v[32:47], v[0:3], v[92:95], 0
	v_exp_f32_e32 v188, v8
	ds_read_b128 v[8:11], v197 offset:33856
	v_sub_f32_e32 v48, 0xf149f2ca, v52
	v_exp_f32_e32 v1, v48
	ds_read_b128 v[48:51], v197 offset:33888
	v_sub_f32_e32 v0, v14, v52
	v_exp_f32_e32 v190, v0
	s_waitcnt lgkmcnt(2)
	v_mfma_f32_32x32x16_bf16 v[32:47], v[4:7], v[88:91], v[32:47]
	v_sub_f32_e32 v0, v15, v52
	v_exp_f32_e32 v156, v0
	v_mul_f32_e32 v0, 0, v1
	v_mov_b32_e32 v1, v0
	v_mov_b32_e32 v2, v0
	v_mov_b32_e32 v3, v0
	v_mov_b32_e32 v4, v0
	s_waitcnt lgkmcnt(1)
	v_mfma_f32_32x32x16_bf16 v[32:47], v[8:11], v[84:87], v[32:47]
	v_mov_b32_e32 v5, v0
	v_mov_b32_e32 v6, v0
	v_mov_b32_e32 v7, v0
	v_mov_b32_e32 v8, v0
	v_mov_b32_e32 v9, v0
	v_mov_b32_e32 v10, v0
	v_mov_b32_e32 v11, v0
	s_waitcnt lgkmcnt(0)
	v_mfma_f32_32x32x16_bf16 v[32:47], v[48:51], v[96:99], v[32:47]
	s_nop 0
	v_mov_b32_e32 v12, v0
	v_cvt_pk_bf16_f32 v200, v192, v198
	v_cvt_pk_bf16_f32 v201, v144, v142
	v_cvt_pk_bf16_f32 v202, v136, v146
	v_cvt_pk_bf16_f32 v203, v150, v152
	s_nop 5
	s_nop 1
	v_max_f32_e32 v13, v32, v33
	s_nop 1
	v_max_f32_e32 v14, v34, v35
	v_max3_f32 v13, v13, s23, v14
	s_nop 1
	v_max_f32_e32 v14, v16, v17
	s_nop 0
	v_max_f32_e32 v15, v18, v19
	v_max3_f32 v13, v13, v14, v15
	s_nop 1
	v_max_f32_e32 v14, v36, v37
	s_nop 1
	v_max_f32_e32 v15, v38, v39
	v_max3_f32 v13, v13, v14, v15
	s_nop 1
	v_max_f32_e32 v14, v20, v21
	s_nop 1
	v_max_f32_e32 v15, v22, v23
	v_max3_f32 v13, v13, v14, v15
	s_nop 1
	v_max_f32_e32 v14, v40, v41
	s_nop 1
	v_max_f32_e32 v15, v42, v43
	v_max3_f32 v13, v13, v14, v15
	s_nop 1
	v_max_f32_e32 v14, v24, v25
	s_nop 1
	v_max_f32_e32 v15, v26, v27
	v_max3_f32 v13, v13, v14, v15
	s_nop 1
	v_max_f32_e32 v14, v44, v45
	s_nop 1
	v_max_f32_e32 v15, v46, v47
	v_max3_f32 v13, v13, v14, v15
	s_nop 1
	v_max_f32_e32 v14, v28, v29
	s_nop 1
	v_max_f32_e32 v15, v30, v31
	v_max3_f32 v48, v13, v14, v15
	ds_bpermute_b32 v49, v210, v48
	v_mov_b32_e32 v13, v0
	v_mov_b32_e32 v14, v0
	v_mov_b32_e32 v15, v0
	s_waitcnt lgkmcnt(0)
	v_max3_f32 v199, v52, v48, v49
	v_sub_f32_e32 v16, v16, v199
	v_exp_f32_e32 v83, v16
	v_sub_f32_e32 v16, v17, v199
	v_exp_f32_e32 v135, v16
	v_sub_f32_e32 v16, v18, v199
	v_exp_f32_e32 v137, v16
	v_sub_f32_e32 v16, v19, v199
	v_exp_f32_e32 v147, v16
	v_sub_f32_e32 v16, v36, v199
	v_exp_f32_e32 v151, v16
	v_sub_f32_e32 v16, v37, v199
	v_exp_f32_e32 v153, v16
	v_sub_f32_e32 v16, v38, v199
	v_exp_f32_e32 v149, v16
	v_sub_f32_e32 v16, v39, v199
	v_exp_f32_e32 v155, v16
	v_sub_f32_e32 v16, v20, v199
	v_exp_f32_e32 v159, v16
	v_sub_f32_e32 v16, v21, v199
	v_sub_f32_e32 v48, v52, v199
	v_mfma_f32_32x32x16_bf16 v[50:65], v[128:131], v[200:203], v[0:15]
	v_exp_f32_e32 v161, v16
	v_mov_b64_e32 v[16:17], v[14:15]
	v_sub_f32_e32 v18, v22, v199
	v_exp_f32_e32 v163, v18
	v_cvt_pk_bf16_f32 v18, v162, v168
	s_nop 1
	v_mov_b64_e32 v[14:15], v[12:13]
	v_mov_b64_e32 v[12:13], v[10:11]
	v_mov_b64_e32 v[10:11], v[8:9]
	v_mov_b64_e32 v[8:9], v[6:7]
	v_mov_b64_e32 v[6:7], v[4:5]
	v_mov_b64_e32 v[4:5], v[2:3]
	v_mov_b64_e32 v[2:3], v[0:1]
	v_cvt_pk_bf16_f32 v19, v164, v166
	v_cvt_pk_bf16_f32 v20, v176, v178
	v_mfma_f32_32x32x16_bf16 v[2:17], v[124:127], v[200:203], v[2:17]
	v_cvt_pk_bf16_f32 v21, v182, v184
	v_sub_f32_e32 v1, v23, v199
	v_exp_f32_e32 v169, v1
	v_sub_f32_e32 v1, v40, v199
	v_cvt_pk_bf16_f32 v22, v186, v188
	v_cvt_pk_bf16_f32 v23, v190, v156
	v_sub_f32_e32 v32, v32, v199
	v_mfma_f32_32x32x16_bf16 v[50:65], v[120:123], v[18:21], v[50:65]
	v_exp_f32_e32 v165, v1
	v_sub_f32_e32 v1, v41, v199
	v_exp_f32_e32 v145, v32
	v_sub_f32_e32 v32, v33, v199
	v_exp_f32_e32 v167, v1
	v_sub_f32_e32 v1, v42, v199
	v_exp_f32_e32 v143, v32
	v_mfma_f32_32x32x16_bf16 v[2:17], v[116:119], v[18:21], v[2:17]
	v_cvt_pk_bf16_f32 v18, v140, v138
	v_cvt_pk_bf16_f32 v19, v82, v134
	v_cvt_pk_bf16_f32 v20, v148, v154
	v_cvt_pk_bf16_f32 v21, v158, v160
	v_sub_f32_e32 v32, v34, v199
	v_exp_f32_e32 v171, v1
	v_sub_f32_e32 v1, v43, v199
	v_mfma_f32_32x32x16_bf16 v[50:65], v[112:115], v[18:21], v[50:65]
	v_exp_f32_e32 v141, v32
	v_sub_f32_e32 v32, v35, v199
	v_exp_f32_e32 v173, v1
	v_sub_f32_e32 v1, v24, v199
	v_exp_f32_e32 v139, v32
	v_exp_f32_e32 v175, v1
	v_sub_f32_e32 v1, v25, v199
	v_mfma_f32_32x32x16_bf16 v[2:17], v[108:111], v[18:21], v[2:17]
	v_cvt_pk_bf16_f32 v20, v170, v172
	v_cvt_pk_bf16_f32 v21, v174, v180
	v_exp_f32_e32 v18, v48
	v_exp_f32_e32 v181, v1
	v_sub_f32_e32 v1, v44, v199
	v_exp_f32_e32 v183, v1
	v_sub_f32_e32 v1, v45, v199
	v_mfma_f32_32x32x16_bf16 v[50:65], v[78:81], v[20:23], v[50:65]
	ds_read_b64_tr_b16 v[78:79], v211 offset:43008
	ds_read_b64_tr_b16 v[80:81], v211 offset:44160
	ds_read_b64_tr_b16 v[110:111], v211 offset:44224
	ds_read_b64_tr_b16 v[108:109], v211 offset:43072
	ds_read_b64_tr_b16 v[112:113], v211 offset:45312
	ds_read_b64_tr_b16 v[114:115], v211 offset:46464
	v_exp_f32_e32 v185, v1
	v_sub_f32_e32 v1, v46, v199
	v_exp_f32_e32 v187, v1
	v_sub_f32_e32 v1, v47, v199
	v_cvt_pk_bf16_f32 v116, v145, v143
	v_cvt_pk_bf16_f32 v117, v141, v139
	v_mfma_f32_32x32x16_bf16 v[2:17], v[74:77], v[20:23], v[2:17]
	v_cvt_pk_bf16_f32 v118, v151, v153
	v_cvt_pk_bf16_f32 v119, v149, v155
	v_mul_f32_e64 v48, v64, v18
	v_mul_f32_e64 v49, v65, v18
	v_mul_f32_e64 v46, v62, v18
	v_mul_f32_e64 v47, v63, v18
	v_pk_mul_f32 v[44:45], v[60:61], v[18:19] op_sel_hi:[1,0]
	v_pk_mul_f32 v[42:43], v[58:59], v[18:19] op_sel_hi:[1,0]
	v_pk_mul_f32 v[40:41], v[56:57], v[18:19] op_sel_hi:[1,0]
	v_pk_mul_f32 v[38:39], v[54:55], v[18:19] op_sel_hi:[1,0]
	v_pk_mul_f32 v[36:37], v[52:53], v[18:19] op_sel_hi:[1,0]
	v_pk_mul_f32 v[34:35], v[50:51], v[18:19] op_sel_hi:[1,0]
	v_pk_mul_f32 v[16:17], v[16:17], v[18:19] op_sel_hi:[1,0]
	v_pk_mul_f32 v[14:15], v[14:15], v[18:19] op_sel_hi:[1,0]
	v_pk_mul_f32 v[12:13], v[12:13], v[18:19] op_sel_hi:[1,0]
	v_pk_mul_f32 v[10:11], v[10:11], v[18:19] op_sel_hi:[1,0]
	v_pk_mul_f32 v[8:9], v[8:9], v[18:19] op_sel_hi:[1,0]
	v_pk_mul_f32 v[6:7], v[6:7], v[18:19] op_sel_hi:[1,0]
	v_pk_mul_f32 v[4:5], v[4:5], v[18:19] op_sel_hi:[1,0]
	v_pk_mul_f32 v[2:3], v[2:3], v[18:19] op_sel_hi:[1,0]
	s_waitcnt lgkmcnt(4)
	v_mfma_f32_32x32x16_bf16 v[34:49], v[78:81], v[116:119], v[34:49]
	v_exp_f32_e32 v189, v1
	ds_read_b64_tr_b16 v[22:23], v211 offset:46528
	ds_read_b64_tr_b16 v[20:21], v211 offset:45376
	v_cvt_pk_bf16_f32 v50, v165, v167
	v_cvt_pk_bf16_f32 v51, v171, v173
	v_cvt_pk_bf16_f32 v52, v183, v185
	v_cvt_pk_bf16_f32 v53, v187, v189
	v_sub_f32_e32 v1, v26, v199
	s_waitcnt lgkmcnt(4)
	v_mfma_f32_32x32x16_bf16 v[2:17], v[108:111], v[116:119], v[2:17]
	v_exp_f32_e32 v177, v1
	v_sub_f32_e32 v1, v27, v199
	ds_read_b64_tr_b16 v[24:25], v211 offset:47616
	ds_read_b64_tr_b16 v[26:27], v211 offset:48768
	v_exp_f32_e32 v179, v1
	v_sub_f32_e32 v1, v28, v199
	v_exp_f32_e32 v191, v1
	v_sub_f32_e32 v1, v29, v199
	s_waitcnt lgkmcnt(4)
	v_mfma_f32_32x32x16_bf16 v[34:49], v[112:115], v[50:53], v[34:49]
	v_exp_f32_e32 v157, v1
	v_sub_f32_e32 v1, v30, v199
	v_sub_f32_e32 v19, v31, v199
	v_exp_f32_e32 v1, v1
	v_exp_f32_e32 v19, v19
	v_cvt_pk_bf16_f32 v28, v175, v181
	v_cvt_pk_bf16_f32 v29, v177, v179
	s_waitcnt lgkmcnt(2)
	v_mfma_f32_32x32x16_bf16 v[2:17], v[20:23], v[50:53], v[2:17]
	ds_read_b64_tr_b16 v[22:23], v211 offset:48832
	ds_read_b64_tr_b16 v[20:21], v211 offset:47680
	v_cvt_pk_bf16_f32 v50, v83, v135
	v_cvt_pk_bf16_f32 v51, v137, v147
	v_cvt_pk_bf16_f32 v52, v159, v161
	v_cvt_pk_bf16_f32 v53, v163, v169
	v_cvt_pk_bf16_f32 v30, v191, v157
	v_cvt_pk_bf16_f32 v31, v1, v19
	s_waitcnt lgkmcnt(2)
	v_mfma_f32_32x32x16_bf16 v[34:49], v[24:27], v[50:53], v[34:49]
	ds_read_b64_tr_b16 v[24:25], v211 offset:49920
	ds_read_b64_tr_b16 v[26:27], v211 offset:51072
	s_waitcnt lgkmcnt(2)
	v_mfma_f32_32x32x16_bf16 v[2:17], v[20:23], v[50:53], v[2:17]
	ds_read_b64_tr_b16 v[22:23], v211 offset:51136
	ds_read_b64_tr_b16 v[20:21], v211 offset:49984
	s_waitcnt vmcnt(3)
	ds_write_b128 v207, v[66:69] offset:15360
	s_waitcnt vmcnt(2)
	ds_write_b128 v207, v[70:73] offset:24576
	s_waitcnt lgkmcnt(0)
	s_barrier
	v_mfma_f32_32x32x16_bf16 v[34:49], v[24:27], v[28:31], v[34:49]
	v_mfma_f32_32x32x16_bf16 v[2:17], v[20:23], v[28:31], v[2:17]
	ds_read_b128 v[20:23], v196 offset:15360
	ds_read_b128 v[24:27], v196 offset:15392
	s_waitcnt lgkmcnt(1)
	v_mfma_f32_32x32x16_bf16 v[52:67], v[20:23], v[92:95], 0
	s_waitcnt lgkmcnt(0)
	v_mfma_f32_32x32x16_bf16 v[52:67], v[24:27], v[88:91], v[52:67]
	ds_read_b128 v[20:23], v196 offset:15424
	ds_read_b128 v[24:27], v196 offset:15456
	s_waitcnt lgkmcnt(1)
	v_mfma_f32_32x32x16_bf16 v[52:67], v[20:23], v[84:87], v[52:67]
	v_add_f32_e32 v20, 0, v192
	v_add_f32_e32 v192, v198, v20
	v_add_f32_e64 v20, v144, v192
	v_add_f32_e64 v21, v145, v193
	v_add_f32_e64 v20, v142, v20
	v_add_f32_e64 v21, v143, v21
	v_pk_add_f32 v[20:21], v[140:141], v[20:21]
	s_waitcnt lgkmcnt(0)
	v_mfma_f32_32x32x16_bf16 v[52:67], v[24:27], v[96:99], v[52:67]
	v_add_f32_e64 v28, v138, v20
	v_add_f32_e64 v29, v139, v21
	ds_read_b128 v[20:23], v197 offset:15360
	v_add_f32_e64 v24, v82, v28
	v_add_f32_e64 v25, v83, v29
	v_pk_add_f32 v[24:25], v[134:135], v[24:25]
	s_nop 0
	v_pk_add_f32 v[24:25], v[136:137], v[24:25]
	s_nop 0
	v_pk_add_f32 v[24:25], v[146:147], v[24:25]
	s_nop 0
	v_pk_add_f32 v[24:25], v[150:151], v[24:25]
	s_nop 0
	v_pk_add_f32 v[28:29], v[152:153], v[24:25]
	ds_read_b128 v[24:27], v197 offset:15392
	s_waitcnt lgkmcnt(1)
	v_mfma_f32_32x32x16_bf16 v[68:83], v[20:23], v[92:95], 0
	v_add_f32_e64 v20, v148, v28
	v_add_f32_e64 v21, v149, v29
	v_add_f32_e64 v20, v154, v20
	v_add_f32_e64 v21, v155, v21
	v_add_f32_e64 v20, v158, v20
	v_add_f32_e64 v21, v159, v21
	v_pk_add_f32 v[20:21], v[160:161], v[20:21]
	s_waitcnt lgkmcnt(0)
	v_mfma_f32_32x32x16_bf16 v[68:83], v[24:27], v[88:91], v[68:83]
	v_add_f32_e64 v20, v162, v20
	v_add_f32_e64 v21, v163, v21
	v_add_f32_e64 v28, v168, v20
	v_add_f32_e64 v29, v169, v21
	ds_read_b128 v[20:23], v197 offset:15424
	v_pk_add_f32 v[24:25], v[164:165], v[28:29]
	s_nop 0
	v_pk_add_f32 v[24:25], v[166:167], v[24:25]
	s_nop 0
	v_pk_add_f32 v[24:25], v[170:171], v[24:25]
	s_nop 0
	v_pk_add_f32 v[24:25], v[172:173], v[24:25]
	s_nop 0
	v_pk_add_f32 v[24:25], v[174:175], v[24:25]
	s_nop 0
	v_pk_add_f32 v[28:29], v[180:181], v[24:25]
	ds_read_b128 v[24:27], v197 offset:15456
	s_waitcnt lgkmcnt(1)
	v_mfma_f32_32x32x16_bf16 v[68:83], v[20:23], v[84:87], v[68:83]
	v_add_f32_e64 v20, v176, v28
	v_add_f32_e64 v21, v177, v29
	v_add_f32_e64 v20, v178, v20
	v_add_f32_e64 v21, v179, v21
	v_add_f32_e64 v20, v182, v20
	v_add_f32_e64 v21, v183, v21
	v_pk_add_f32 v[20:21], v[184:185], v[20:21]
	s_waitcnt lgkmcnt(0)
	v_mfma_f32_32x32x16_bf16 v[68:83], v[24:27], v[96:99], v[68:83]
	s_nop 0
	v_add_f32_e64 v20, v186, v20
	v_add_f32_e64 v21, v187, v21
	v_add_f32_e64 v20, v188, v20
	v_add_f32_e64 v21, v189, v21
	v_pk_add_f32 v[20:21], v[190:191], v[20:21]
	s_nop 5
	s_nop 1
	v_max_f32_e32 v22, v68, v69
	s_nop 1
	v_max_f32_e32 v23, v70, v71
	v_max3_f32 v22, v22, s23, v23
	s_nop 1
	v_max_f32_e32 v23, v52, v53
	s_nop 0
	v_max_f32_e32 v24, v54, v55
	v_max3_f32 v22, v22, v23, v24
	s_nop 1
	v_max_f32_e32 v23, v72, v73
	s_nop 1
	v_max_f32_e32 v24, v74, v75
	v_max3_f32 v22, v22, v23, v24
	s_nop 1
	v_max_f32_e32 v23, v56, v57
	s_nop 1
	v_max_f32_e32 v24, v58, v59
	v_max3_f32 v22, v22, v23, v24
	s_nop 1
	v_max_f32_e32 v23, v76, v77
	s_nop 1
	v_max_f32_e32 v24, v78, v79
	v_max3_f32 v22, v22, v23, v24
	s_nop 1
	v_max_f32_e32 v23, v60, v61
	s_nop 1
	v_max_f32_e32 v24, v62, v63
	v_max3_f32 v22, v22, v23, v24
	s_nop 1
	v_max_f32_e32 v23, v80, v81
	s_nop 1
	v_max_f32_e32 v24, v82, v83
	v_max3_f32 v22, v22, v23, v24
	s_nop 1
	v_max_f32_e32 v23, v64, v65
	s_nop 1
	v_max_f32_e32 v24, v66, v67
	v_max3_f32 v22, v22, v23, v24
	ds_bpermute_b32 v23, v210, v22
	v_pk_add_f32 v[20:21], v[156:157], v[20:21]
	s_waitcnt lgkmcnt(0)
	v_max3_f32 v125, v199, v22, v23
	v_pk_add_f32 v[0:1], v[0:1], v[20:21]
	v_sub_f32_e32 v22, v58, v125
	v_add_f32_e32 v1, v1, v19
	v_sub_f32_e32 v19, v68, v125
	v_fmac_f32_e32 v1, v0, v18
	v_sub_f32_e32 v18, v55, v125
	v_exp_f32_e32 v127, v19
	v_sub_f32_e32 v19, v69, v125
	v_exp_f32_e32 v124, v18
	v_sub_f32_e32 v18, v72, v125
	v_exp_f32_e32 v129, v19
	v_exp_f32_e32 v126, v18
	v_sub_f32_e32 v18, v73, v125
	v_exp_f32_e32 v128, v18
	v_sub_f32_e32 v18, v74, v125
	v_exp_f32_e32 v144, v18
	v_sub_f32_e32 v18, v75, v125
	v_add_f32_e32 v0, 0, v127
	v_exp_f32_e32 v146, v18
	v_sub_f32_e32 v18, v56, v125
	v_add_f32_e32 v192, v129, v0
	v_sub_f32_e32 v0, v70, v125
	v_exp_f32_e32 v130, v18
	v_sub_f32_e32 v18, v57, v125
	v_exp_f32_e32 v136, v0
	v_sub_f32_e32 v0, v71, v125
	v_exp_f32_e32 v134, v18
	ds_read_b64_tr_b16 v[164:165], v211 offset:24576
	ds_read_b64_tr_b16 v[166:167], v211 offset:25728
	ds_read_b64_tr_b16 v[170:171], v211 offset:25792
	ds_read_b64_tr_b16 v[168:169], v211 offset:24640
	ds_read_b64_tr_b16 v[120:121], v211 offset:26880
	ds_read_b64_tr_b16 v[122:123], v211 offset:28032
	ds_read_b64_tr_b16 v[114:115], v211 offset:28096
	ds_read_b64_tr_b16 v[112:113], v211 offset:26944
	ds_read_b64_tr_b16 v[116:117], v211 offset:29184
	ds_read_b64_tr_b16 v[118:119], v211 offset:30336
	ds_read_b64_tr_b16 v[110:111], v211 offset:30400
	ds_read_b64_tr_b16 v[108:109], v211 offset:29248
	ds_read_b64_tr_b16 v[72:73], v211 offset:31488
	ds_read_b64_tr_b16 v[74:75], v211 offset:32640
	ds_read_b64_tr_b16 v[70:71], v211 offset:32704
	ds_read_b64_tr_b16 v[68:69], v211 offset:31552
	s_waitcnt vmcnt(1)
	ds_write_b128 v207, v[100:103] offset:33792
	s_waitcnt vmcnt(0)
	ds_write_b128 v207, v[104:107] offset:43008
	s_waitcnt lgkmcnt(0)
	s_barrier
	ds_read_b128 v[18:21], v196 offset:33792
	v_exp_f32_e32 v100, v22
	v_sub_f32_e32 v22, v59, v125
	v_exp_f32_e32 v138, v0
	v_sub_f32_e32 v0, v52, v125
	v_exp_f32_e32 v102, v22
	v_sub_f32_e32 v22, v76, v125
	v_exp_f32_e32 v140, v0
	v_sub_f32_e32 v0, v53, v125
	v_exp_f32_e32 v76, v22
	v_sub_f32_e32 v22, v77, v125
	ds_read_b128 v[50:53], v196 offset:33824
	v_exp_f32_e32 v104, v22
	s_waitcnt lgkmcnt(1)
	v_mfma_f32_32x32x16_bf16 v[18:33], v[18:21], v[92:95], 0
	v_exp_f32_e32 v142, v0
	v_sub_f32_e32 v0, v54, v125
	v_sub_f32_e32 v54, v78, v125
	v_exp_f32_e32 v150, v54
	v_sub_f32_e32 v54, v79, v125
	v_exp_f32_e32 v154, v54
	v_sub_f32_e32 v54, v60, v125
	v_exp_f32_e32 v158, v54
	ds_read_b128 v[54:57], v196 offset:33856
	s_waitcnt lgkmcnt(1)
	v_mfma_f32_32x32x16_bf16 v[18:33], v[50:53], v[88:91], v[18:33]
	v_sub_f32_e32 v50, v61, v125
	v_exp_f32_e32 v162, v50
	v_sub_f32_e32 v50, v62, v125
	v_exp_f32_e32 v78, v50
	v_sub_f32_e32 v50, v63, v125
	v_exp_f32_e32 v106, v50
	ds_read_b128 v[50:53], v196 offset:33888
	s_waitcnt lgkmcnt(1)
	v_mfma_f32_32x32x16_bf16 v[18:33], v[54:57], v[84:87], v[18:33]
	v_sub_f32_e32 v54, v80, v125
	v_exp_f32_e32 v80, v54
	v_sub_f32_e32 v54, v81, v125
	v_exp_f32_e32 v148, v54
	v_sub_f32_e32 v54, v82, v125
	v_exp_f32_e32 v82, v54
	ds_read_b128 v[54:57], v197 offset:33792
	ds_read_b128 v[172:175], v197 offset:33824
	s_waitcnt lgkmcnt(2)
	v_mfma_f32_32x32x16_bf16 v[18:33], v[50:53], v[96:99], v[18:33]
	v_sub_f32_e32 v50, v83, v125
	v_exp_f32_e32 v152, v50
	v_sub_f32_e32 v50, v64, v125
	v_exp_f32_e32 v156, v50
	v_sub_f32_e32 v50, v65, v125
	v_exp_f32_e32 v160, v50
	ds_read_b128 v[176:179], v197 offset:33856
	s_waitcnt lgkmcnt(2)
	v_mfma_f32_32x32x16_bf16 v[50:65], v[54:57], v[92:95], 0
	v_sub_f32_e32 v131, v199, v125
	v_exp_f32_e32 v180, v131
	v_sub_f32_e32 v67, v67, v125
	v_exp_f32_e32 v94, v67
	s_nop 0
	v_mul_f32_e32 v92, v1, v180
	v_pk_mul_f32 v[48:49], v[48:49], v[180:181] op_sel_hi:[1,0]
	s_waitcnt lgkmcnt(1)
	v_mfma_f32_32x32x16_bf16 v[50:65], v[172:175], v[88:91], v[50:65]
	ds_read_b128 v[88:91], v197 offset:33888
	v_mul_f32_e64 v46, v46, v180
	v_mul_f32_e64 v47, v47, v180
	v_mul_f32_e64 v44, v44, v180
	v_mul_f32_e64 v45, v45, v180
	v_pk_mul_f32 v[42:43], v[42:43], v[180:181] op_sel_hi:[1,0]
	v_pk_mul_f32 v[40:41], v[40:41], v[180:181] op_sel_hi:[1,0]
	v_pk_mul_f32 v[38:39], v[38:39], v[180:181] op_sel_hi:[1,0]
	v_pk_mul_f32 v[36:37], v[36:37], v[180:181] op_sel_hi:[1,0]
	s_waitcnt lgkmcnt(1)
	v_mfma_f32_32x32x16_bf16 v[50:65], v[176:179], v[84:87], v[50:65]
	v_mul_f32_e64 v34, v34, v180
	v_mul_f32_e64 v35, v35, v180
	v_mul_f32_e64 v16, v16, v180
	v_mul_f32_e64 v17, v17, v180
	v_mul_f32_e64 v14, v14, v180
	v_mul_f32_e64 v15, v15, v180
	v_pk_mul_f32 v[12:13], v[12:13], v[180:181] op_sel_hi:[1,0]
	v_pk_mul_f32 v[10:11], v[10:11], v[180:181] op_sel_hi:[1,0]
	v_pk_mul_f32 v[8:9], v[8:9], v[180:181] op_sel_hi:[1,0]
	v_pk_mul_f32 v[6:7], v[6:7], v[180:181] op_sel_hi:[1,0]
	s_waitcnt lgkmcnt(0)
	v_mfma_f32_32x32x16_bf16 v[50:65], v[88:91], v[96:99], v[50:65]
	v_mul_f32_e64 v4, v4, v180
	v_mul_f32_e64 v5, v5, v180
	v_mul_f32_e64 v2, v2, v180
	v_mul_f32_e64 v3, v3, v180
	v_cvt_pk_bf16_f32 v84, v127, v129
	v_cvt_pk_bf16_f32 v85, v136, v138
	v_cvt_pk_bf16_f32 v86, v126, v128
	v_cvt_pk_bf16_f32 v87, v144, v146
	v_sub_f32_e32 v66, v66, v125
	s_nop 2
	s_nop 1
	v_max_f32_e32 v1, v50, v51
	s_nop 1
	v_max_f32_e32 v67, v52, v53
	v_max3_f32 v1, v1, s23, v67
	s_nop 1
	v_max_f32_e32 v67, v18, v19
	s_nop 0
	v_max_f32_e32 v77, v20, v21
	v_max3_f32 v1, v1, v67, v77
	s_nop 1
	v_max_f32_e32 v67, v54, v55
	s_nop 1
	v_max_f32_e32 v77, v56, v57
	v_max3_f32 v1, v1, v67, v77
	s_nop 1
	v_max_f32_e32 v67, v22, v23
	s_nop 1
	v_max_f32_e32 v77, v24, v25
	v_max3_f32 v1, v1, v67, v77
	s_nop 1
	v_max_f32_e32 v67, v58, v59
	s_nop 1
	v_max_f32_e32 v77, v60, v61
	v_max3_f32 v1, v1, v67, v77
	s_nop 1
	v_max_f32_e32 v67, v26, v27
	s_nop 1
	v_max_f32_e32 v77, v28, v29
	v_max3_f32 v1, v1, v67, v77
	s_nop 1
	v_max_f32_e32 v67, v62, v63
	s_nop 1
	v_max_f32_e32 v77, v64, v65
	v_max3_f32 v1, v1, v67, v77
	s_nop 1
	v_max_f32_e32 v67, v30, v31
	s_nop 1
	v_max_f32_e32 v77, v32, v33
	v_max3_f32 v1, v1, v67, v77
	ds_bpermute_b32 v67, v210, v1
	v_mfma_f32_32x32x16_bf16 v[34:49], v[164:167], v[84:87], v[34:49]
	v_exp_f32_e32 v0, v0
	v_exp_f32_e32 v66, v66
	s_waitcnt lgkmcnt(0)
	v_max3_f32 v96, v125, v1, v67
	v_sub_f32_e32 v1, v50, v96
	v_exp_f32_e32 v137, v1
	v_sub_f32_e32 v1, v51, v96
	v_mfma_f32_32x32x16_bf16 v[2:17], v[168:171], v[84:87], v[2:17]
	v_exp_f32_e32 v139, v1
	v_sub_f32_e32 v1, v52, v96
	v_exp_f32_e32 v141, v1
	v_sub_f32_e32 v1, v53, v96
	v_exp_f32_e32 v143, v1
	v_sub_f32_e32 v1, v18, v96
	v_sub_f32_e32 v18, v19, v96
	v_sub_f32_e32 v67, v125, v96
	v_exp_f32_e32 v125, v18
	v_sub_f32_e32 v18, v20, v96
	v_exp_f32_e32 v127, v18
	v_sub_f32_e32 v18, v21, v96
	v_exp_f32_e32 v129, v18
	v_sub_f32_e32 v18, v54, v96
	v_exp_f32_e32 v1, v1
	v_exp_f32_e32 v145, v18
	v_pk_add_f32 v[18:19], v[136:137], v[192:193]
	v_cvt_pk_bf16_f32 v50, v76, v104
	v_cvt_pk_bf16_f32 v51, v150, v154
	v_cvt_pk_bf16_f32 v52, v80, v148
	v_cvt_pk_bf16_f32 v53, v82, v152
	v_pk_add_f32 v[18:19], v[138:139], v[18:19]
	v_cvt_pk_bf16_f32 v21, v0, v124
	v_mfma_f32_32x32x16_bf16 v[34:49], v[120:123], v[50:53], v[34:49]
	v_add_f32_e64 v18, v140, v18
	v_add_f32_e64 v19, v141, v19
	v_cvt_pk_bf16_f32 v20, v140, v142
	v_add_f32_e64 v18, v142, v18
	v_add_f32_e64 v19, v143, v19
	v_lshlrev_b32_e32 v192, 1, v206
	v_pk_add_f32 v[18:19], v[0:1], v[18:19]
	v_sub_f32_e32 v0, v55, v96
	v_exp_f32_e32 v147, v0
	v_mfma_f32_32x32x16_bf16 v[2:17], v[112:115], v[50:53], v[2:17]
	v_sub_f32_e32 v0, v56, v96
	v_exp_f32_e32 v131, v0
	v_sub_f32_e32 v0, v57, v96
	v_exp_f32_e32 v135, v0
	v_sub_f32_e32 v0, v22, v96
	v_exp_f32_e32 v101, v0
	v_sub_f32_e32 v0, v23, v96
	v_cvt_pk_bf16_f32 v22, v130, v134
	v_cvt_pk_bf16_f32 v23, v100, v102
	v_exp_f32_e32 v103, v0
	v_sub_f32_e32 v0, v24, v96
	v_mfma_f32_32x32x16_bf16 v[34:49], v[116:119], v[20:23], v[34:49]
	v_exp_f32_e32 v77, v0
	v_sub_f32_e32 v0, v25, v96
	v_exp_f32_e32 v105, v0
	v_sub_f32_e32 v0, v58, v96
	v_exp_f32_e32 v151, v0
	v_sub_f32_e32 v0, v59, v96
	v_exp_f32_e32 v155, v0
	v_mfma_f32_32x32x16_bf16 v[2:17], v[108:111], v[20:23], v[2:17]
	v_sub_f32_e32 v0, v60, v96
	v_exp_f32_e32 v159, v0
	v_sub_f32_e32 v0, v61, v96
	v_exp_f32_e32 v163, v0
	v_sub_f32_e32 v0, v26, v96
	v_cvt_pk_bf16_f32 v24, v158, v162
	v_exp_f32_e32 v79, v0
	v_sub_f32_e32 v0, v27, v96
	v_cvt_pk_bf16_f32 v25, v78, v106
	v_cvt_pk_bf16_f32 v26, v156, v160
	v_cvt_pk_bf16_f32 v27, v66, v94
	v_exp_f32_e32 v107, v0
	v_sub_f32_e32 v0, v28, v96
	v_mfma_f32_32x32x16_bf16 v[34:49], v[72:75], v[24:27], v[34:49]
	v_exp_f32_e32 v81, v0
	v_sub_f32_e32 v0, v29, v96
	v_pk_add_f32 v[18:19], v[124:125], v[18:19]
	v_exp_f32_e32 v149, v0
	v_sub_f32_e32 v0, v62, v96
	v_pk_add_f32 v[18:19], v[126:127], v[18:19]
	v_exp_f32_e32 v83, v0
	v_mfma_f32_32x32x16_bf16 v[2:17], v[68:71], v[24:27], v[2:17]
	v_sub_f32_e32 v0, v63, v96
	v_sub_f32_e32 v20, v64, v96
	v_add_f32_e64 v18, v128, v18
	v_add_f32_e64 v19, v129, v19
	v_exp_f32_e32 v153, v0
	v_exp_f32_e32 v0, v67
	v_exp_f32_e32 v157, v20
	ds_read_b64_tr_b16 v[20:21], v211 offset:43008
	ds_read_b64_tr_b16 v[22:23], v211 offset:44160
	ds_read_b64_tr_b16 v[26:27], v211 offset:44224
	ds_read_b64_tr_b16 v[24:25], v211 offset:43072
	v_lshlrev_b64 v[28:29], 11, v[132:133]
	v_pk_add_f32 v[18:19], v[144:145], v[18:19]
	v_lshl_add_u64 v[28:29], s[0:1], 0, v[28:29]
	v_pk_add_f32 v[18:19], v[146:147], v[18:19]
	v_lshl_add_u64 v[28:29], v[28:29], 0, s[16:17]
	v_pk_add_f32 v[18:19], v[130:131], v[18:19]
	v_lshl_add_u64 v[28:29], v[28:29], 0, v[192:193]
	v_pk_add_f32 v[18:19], v[134:135], v[18:19]
	v_pk_mul_f32 v[48:49], v[48:49], v[0:1] op_sel_hi:[1,0]
	v_pk_mul_f32 v[46:47], v[46:47], v[0:1] op_sel_hi:[1,0]
	v_pk_mul_f32 v[44:45], v[44:45], v[0:1] op_sel_hi:[1,0]
	v_pk_mul_f32 v[42:43], v[42:43], v[0:1] op_sel_hi:[1,0]
	v_pk_mul_f32 v[40:41], v[40:41], v[0:1] op_sel_hi:[1,0]
	v_pk_mul_f32 v[38:39], v[38:39], v[0:1] op_sel_hi:[1,0]
	v_pk_mul_f32 v[36:37], v[36:37], v[0:1] op_sel_hi:[1,0]
	v_pk_mul_f32 v[34:35], v[34:35], v[0:1] op_sel_hi:[1,0]
	v_pk_mul_f32 v[16:17], v[16:17], v[0:1] op_sel_hi:[1,0]
	v_cvt_pk_bf16_f32 v50, v137, v139
	v_cvt_pk_bf16_f32 v51, v141, v143
	v_cvt_pk_bf16_f32 v52, v145, v147
	ds_read_b64_tr_b16 v[54:55], v211 offset:45312
	ds_read_b64_tr_b16 v[56:57], v211 offset:46464
	ds_read_b64_tr_b16 v[60:61], v211 offset:46528
	ds_read_b64_tr_b16 v[58:59], v211 offset:45376
	ds_read_b64_tr_b16 v[68:69], v211 offset:47616
	ds_read_b64_tr_b16 v[70:71], v211 offset:48768
	ds_read_b64_tr_b16 v[74:75], v211 offset:48832
	ds_read_b64_tr_b16 v[72:73], v211 offset:47680
	ds_read_b64_tr_b16 v[84:85], v211 offset:49920
	ds_read_b64_tr_b16 v[86:87], v211 offset:51072
	ds_read_b64_tr_b16 v[90:91], v211 offset:51136
	ds_read_b64_tr_b16 v[88:89], v211 offset:49984
	s_waitcnt lgkmcnt(0)
	s_barrier
	v_mov_b64_e32 v[62:63], v[238:239]
	v_cvt_pk_bf16_f32 v53, v131, v135
	v_pk_mul_f32 v[14:15], v[14:15], v[0:1] op_sel_hi:[1,0]
	v_pk_mul_f32 v[12:13], v[12:13], v[0:1] op_sel_hi:[1,0]
	v_pk_mul_f32 v[10:11], v[10:11], v[0:1] op_sel_hi:[1,0]
	v_pk_mul_f32 v[8:9], v[8:9], v[0:1] op_sel_hi:[1,0]
	v_pk_mul_f32 v[6:7], v[6:7], v[0:1] op_sel_hi:[1,0]
	v_pk_mul_f32 v[4:5], v[4:5], v[0:1] op_sel_hi:[1,0]
	v_pk_mul_f32 v[2:3], v[2:3], v[0:1] op_sel_hi:[1,0]
	v_pk_add_f32 v[18:19], v[100:101], v[18:19]
	v_mfma_f32_32x32x16_bf16 v[34:49], v[20:23], v[50:53], v[34:49]
	v_add_f32_e64 v18, v102, v18
	v_add_f32_e64 v19, v103, v19
	v_sub_f32_e32 v20, v65, v96
	v_add_f32_e64 v18, v76, v18
	v_add_f32_e64 v19, v77, v19
	v_exp_f32_e32 v161, v20
	v_pk_add_f32 v[18:19], v[104:105], v[18:19]
	v_cvt_pk_bf16_f32 v20, v151, v155
	v_pk_add_f32 v[18:19], v[150:151], v[18:19]
	v_mfma_f32_32x32x16_bf16 v[2:17], v[24:27], v[50:53], v[2:17]
	v_mov_b64_e32 v[24:25], v[240:241]
	v_add_f32_e64 v18, v154, v18
	v_add_f32_e64 v19, v155, v19
	v_sub_f32_e32 v26, v30, v96
	v_add_f32_e64 v18, v158, v18
	v_add_f32_e64 v19, v159, v19
	v_cvt_pk_bf16_f32 v21, v159, v163
	v_pk_add_f32 v[18:19], v[162:163], v[18:19]
	v_cvt_pk_bf16_f32 v22, v83, v153
	v_cvt_pk_bf16_f32 v23, v157, v161
	v_exp_f32_e32 v67, v26
	v_mov_b64_e32 v[26:27], v[242:243]
	v_mfma_f32_32x32x16_bf16 v[34:49], v[54:57], v[20:23], v[34:49]
	v_sub_f32_e32 v30, v31, v96
	v_exp_f32_e32 v95, v30
	v_sub_f32_e32 v30, v32, v96
	v_exp_f32_e32 v93, v30
	v_sub_f32_e32 v30, v33, v96
	v_exp_f32_e32 v50, v30
	v_mov_b64_e32 v[30:31], v[244:245]
	v_mfma_f32_32x32x16_bf16 v[2:17], v[58:61], v[20:23], v[2:17]
	v_add_f32_e64 v22, v78, v18
	v_add_f32_e64 v23, v79, v19
	v_cvt_pk_bf16_f32 v18, v1, v125
	v_add_f32_e64 v22, v106, v22
	v_add_f32_e64 v23, v107, v23
	v_cvt_pk_bf16_f32 v19, v127, v129
	v_pk_add_f32 v[22:23], v[80:81], v[22:23]
	v_cvt_pk_bf16_f32 v20, v101, v103
	v_pk_add_f32 v[22:23], v[148:149], v[22:23]
	v_cvt_pk_bf16_f32 v21, v77, v105
	v_pk_add_f32 v[22:23], v[82:83], v[22:23]
	v_mov_b64_e32 v[32:33], v[246:247]
	v_pk_add_f32 v[22:23], v[152:153], v[22:23]
	v_mfma_f32_32x32x16_bf16 v[34:49], v[68:71], v[18:21], v[34:49]
	v_add_f32_e64 v22, v156, v22
	v_add_f32_e64 v23, v157, v23
	s_mov_b32 s0, s16
	v_add_f32_e64 v22, v160, v22
	v_add_f32_e64 v23, v161, v23
	v_writelane_b32 v255, s0, 35
	s_nop 1
	v_writelane_b32 v255, s1, 36
	v_mfma_f32_32x32x16_bf16 v[2:17], v[72:75], v[18:21], v[2:17]
	v_add_f32_e64 v18, v66, v22
	v_add_f32_e64 v19, v67, v23
	v_cvt_pk_bf16_f32 v20, v67, v95
	v_add_f32_e64 v18, v94, v18
	v_add_f32_e64 v19, v95, v19
	v_cvt_pk_bf16_f32 v21, v93, v50
	v_pk_add_f32 v[22:23], v[92:93], v[18:19]
	v_cvt_pk_bf16_f32 v18, v79, v107
	v_add_f32_e32 v23, v23, v50
	v_fmac_f32_e32 v23, v22, v0
	v_mov_b64_e32 v[0:1], v[248:249]
	v_cvt_pk_bf16_f32 v19, v81, v149
	ds_bpermute_b32 v22, v210, v23
	s_waitcnt lgkmcnt(0)
	v_add_f32_e32 v22, v23, v22
	v_mfma_f32_32x32x16_bf16 v[34:49], v[84:87], v[18:21], v[34:49]
	v_div_scale_f32 v23, s[0:1], v22, v22, 1.0
	v_rcp_f32_e32 v50, v23
	s_nop 0
	v_fma_f32 v51, -v23, v50, 1.0
	v_mfma_f32_32x32x16_bf16 v[2:17], v[88:91], v[18:21], v[2:17]
	v_mov_b64_e32 v[18:19], v[224:225]
	v_mov_b64_e32 v[20:21], v[226:227]
	v_fmac_f32_e32 v50, v51, v50
	v_div_scale_f32 v51, vcc, 1.0, v22, 1.0
	v_mul_f32_e32 v52, v51, v50
	v_fma_f32 v53, -v23, v52, v51
	v_fmac_f32_e32 v52, v53, v50
	v_fma_f32 v23, -v23, v52, v51
	v_div_fmas_f32 v23, v23, v50, v52
	v_div_fixup_f32 v22, v23, v22, 1.0
	v_pk_mul_f32 v[34:35], v[34:35], v[22:23] op_sel_hi:[1,0]
	s_waitcnt vmcnt(7)
	v_lshlrev_b32_e32 v50, 16, v62
	v_and_b32_e32 v51, 0xffff0000, v62
	v_pk_mul_f32 v[34:35], v[34:35], v[50:51]
	v_pk_mul_f32 v[36:37], v[36:37], v[22:23] op_sel_hi:[1,0]
	v_lshlrev_b32_e32 v50, 16, v63
	v_and_b32_e32 v51, 0xffff0000, v63
	v_pk_mul_f32 v[36:37], v[36:37], v[50:51]
	v_cvt_pk_bf16_f32 v34, v34, v35
	v_cvt_pk_bf16_f32 v35, v36, v37
	global_store_dwordx2 v[28:29], v[34:35], off
	v_pk_mul_f32 v[34:35], v[38:39], v[22:23] op_sel_hi:[1,0]
	s_waitcnt vmcnt(7)
	v_lshlrev_b32_e32 v36, 16, v24
	v_and_b32_e32 v37, 0xffff0000, v24
	v_pk_mul_f32 v[34:35], v[34:35], v[36:37]
	v_lshlrev_b32_e32 v36, 16, v25
	v_cvt_pk_bf16_f32 v24, v34, v35
	v_pk_mul_f32 v[34:35], v[40:41], v[22:23] op_sel_hi:[1,0]
	v_and_b32_e32 v37, 0xffff0000, v25
	v_pk_mul_f32 v[34:35], v[34:35], v[36:37]
	v_pk_mul_f32 v[2:3], v[2:3], v[22:23] op_sel_hi:[1,0]
	v_cvt_pk_bf16_f32 v25, v34, v35
	global_store_dwordx2 v[28:29], v[24:25], off offset:16
	v_pk_mul_f32 v[24:25], v[42:43], v[22:23] op_sel_hi:[1,0]
	s_waitcnt vmcnt(7)
	v_lshlrev_b32_e32 v34, 16, v26
	v_and_b32_e32 v35, 0xffff0000, v26
	v_pk_mul_f32 v[24:25], v[24:25], v[34:35]
	v_pk_mul_f32 v[34:35], v[44:45], v[22:23] op_sel_hi:[1,0]
	v_lshlrev_b32_e32 v26, 16, v27
	v_and_b32_e32 v27, 0xffff0000, v27
	v_pk_mul_f32 v[26:27], v[34:35], v[26:27]
	v_cvt_pk_bf16_f32 v24, v24, v25
	v_cvt_pk_bf16_f32 v25, v26, v27
	global_store_dwordx2 v[28:29], v[24:25], off offset:32
	v_pk_mul_f32 v[24:25], v[46:47], v[22:23] op_sel_hi:[1,0]
	s_waitcnt vmcnt(7)
	v_lshlrev_b32_e32 v26, 16, v30
	v_and_b32_e32 v27, 0xffff0000, v30
	v_pk_mul_f32 v[24:25], v[24:25], v[26:27]
	v_pk_mul_f32 v[26:27], v[48:49], v[22:23] op_sel_hi:[1,0]
	v_lshlrev_b32_e32 v30, 16, v31
	v_and_b32_e32 v31, 0xffff0000, v31
	v_pk_mul_f32 v[26:27], v[26:27], v[30:31]
	v_cvt_pk_bf16_f32 v24, v24, v25
	v_cvt_pk_bf16_f32 v25, v26, v27
	global_store_dwordx2 v[28:29], v[24:25], off offset:48
	s_waitcnt vmcnt(7)
	v_lshlrev_b32_e32 v24, 16, v32
	v_and_b32_e32 v25, 0xffff0000, v32
	v_pk_mul_f32 v[2:3], v[2:3], v[24:25]
	v_pk_mul_f32 v[4:5], v[4:5], v[22:23] op_sel_hi:[1,0]
	v_lshlrev_b32_e32 v24, 16, v33
	v_and_b32_e32 v25, 0xffff0000, v33
	v_pk_mul_f32 v[4:5], v[4:5], v[24:25]
	v_cvt_pk_bf16_f32 v2, v2, v3
	v_cvt_pk_bf16_f32 v3, v4, v5
	global_store_dwordx2 v[28:29], v[2:3], off offset:64
	v_pk_mul_f32 v[2:3], v[6:7], v[22:23] op_sel_hi:[1,0]
	s_waitcnt vmcnt(7)
	v_lshlrev_b32_e32 v4, 16, v0
	v_and_b32_e32 v5, 0xffff0000, v0
	v_pk_mul_f32 v[2:3], v[2:3], v[4:5]
	v_lshlrev_b32_e32 v4, 16, v1
	v_cvt_pk_bf16_f32 v0, v2, v3
	v_pk_mul_f32 v[2:3], v[8:9], v[22:23] op_sel_hi:[1,0]
	v_and_b32_e32 v5, 0xffff0000, v1
	v_pk_mul_f32 v[2:3], v[2:3], v[4:5]
	s_waitcnt vmcnt(6)
	v_lshlrev_b32_e32 v4, 16, v19
	v_cvt_pk_bf16_f32 v1, v2, v3
	global_store_dwordx2 v[28:29], v[0:1], off offset:80
	v_pk_mul_f32 v[0:1], v[10:11], v[22:23] op_sel_hi:[1,0]
	v_lshlrev_b32_e32 v2, 16, v18
	v_and_b32_e32 v3, 0xffff0000, v18
	v_pk_mul_f32 v[0:1], v[0:1], v[2:3]
	v_pk_mul_f32 v[2:3], v[12:13], v[22:23] op_sel_hi:[1,0]
	v_and_b32_e32 v5, 0xffff0000, v19
	v_pk_mul_f32 v[2:3], v[2:3], v[4:5]
	v_cvt_pk_bf16_f32 v0, v0, v1
	v_cvt_pk_bf16_f32 v1, v2, v3
	global_store_dwordx2 v[28:29], v[0:1], off offset:96
	v_pk_mul_f32 v[0:1], v[14:15], v[22:23] op_sel_hi:[1,0]
	s_waitcnt vmcnt(7)
	v_lshlrev_b32_e32 v2, 16, v20
	v_and_b32_e32 v3, 0xffff0000, v20
	v_pk_mul_f32 v[0:1], v[0:1], v[2:3]
	v_pk_mul_f32 v[2:3], v[16:17], v[22:23] op_sel_hi:[1,0]
	v_lshlrev_b32_e32 v4, 16, v21
	v_and_b32_e32 v5, 0xffff0000, v21
	v_pk_mul_f32 v[2:3], v[2:3], v[4:5]
	v_cvt_pk_bf16_f32 v0, v0, v1
	v_cvt_pk_bf16_f32 v1, v2, v3
	global_store_dwordx2 v[28:29], v[0:1], off offset:112
